# GEMM K-loops: removed the setprio 0/1 flip in the middle of each 32-MFMA block (24 sites); v004 base
# speedup vs baseline: 1.0169x; 1.0009x over previous
; #define PG8_STAGE(bufoff, gbase, voff) do { _Pragma("unroll") for (int _i = 0; _i < 2; ++_i) \
;         __builtin_amdgcn_global_load_lds((const unsigned*)((const char*)(gbase) + (voff)[_i]), (PG8_LAS unsigned*)(lds + (bufoff) + ldsw + _i * 8192), 16, 0, 0); } while (0)
; #define PG8_LDA(dst, b, h) do { _Pragma("unroll") for (int m = 0; m < 4; ++m) _Pragma("unroll") for (int k = 0; k < 2; ++k) dst[m][k] = *(const PG8_LAS bf16x8*)(lds + PG8_SA(b, h) + aoff + m * 2048 + k * 1024); } while (0)
; #define PG8_LDB(dst, b, h) do { _Pragma("unroll") for (int n = 0; n < 2; ++n) _Pragma("unroll") for (int k = 0; k < 2; ++k) dst[n][k] = *(const PG8_LAS bf16x8*)(lds + PG8_SB(b, h) + boff + n * 2048 + k * 1024); } while (0)
; #define PG8_MMA(ai, bj, At, Bt) do { __builtin_amdgcn_s_setprio(1); _Pragma("unroll") for (int m = 0; m < 4; ++m) _Pragma("unroll") for (int n = 0; n < 2; ++n) _Pragma("unroll") for (int k = 0; k < 2; ++k) \
;         acc[ai][bj][m][n] = __builtin_amdgcn_mfma_f32_16x16x32_bf16(Bt[n][k], At[m][k], acc[ai][bj][m][n], 0, 0, 0); __builtin_amdgcn_s_setprio(0); } while (0)
; #define PG8_WAIT_V(n) asm volatile("s_waitcnt vmcnt(" #n ")" ::: "memory")
; #define PG8_WAIT_L(n) asm volatile("s_waitcnt lgkmcnt(" #n ")" ::: "memory")
; #define PG8_BAR __builtin_amdgcn_s_barrier()
; #define PG8_SCHED __builtin_amdgcn_sched_barrier(0)
; template <class Epi, class Sched, bool ALIGN_EPI = false, bool SP2 = false>
; __device__ __forceinline__ void gemm_phase(PG8_LAS unsigned char* lds, const Gemm g, const Sched& S, const Epi& E) {
;     ...
;             const bool last = (t == nt - 2);
;             const char* a1 = cA + (size_t)(t + 1) * kstep;
;             const char* a2 = last ? nA : cA + (size_t)(t + 2) * kstep; const char* b2 = last ? nB : cB + (size_t)(t + 2) * kstep;
;             const char* a3 = a2 + kstep; const char* b3 = b2 + kstep;
;             if (last && has_next) S.a_ready(nxt);
;             if constexpr (SP2) {
;             PG8_LDB(B0, 0, 0); PG8_LDB(B1, 0, 1); PG8_SCHED; PG8_LDA(At, 0, 0); PG8_STAGE(PG8_SA(1, 1), a1 + hstepA, voffA);
;             PG8_WAIT_V(8); PG8_WAIT_L(0); PG8_BAR; PG8_MMA(0, 0, At, B0); PG8_MMA(0, 1, At, B1); PG8_BAR; PG8_SCHED;
;             PG8_LDA(At, 0, 1); PG8_STAGE(PG8_SB(0, 0), b2, voffB); PG8_STAGE(PG8_SB(0, 1), b2 + hstepB, voffB); PG8_STAGE(PG8_SA(0, 0), a2, voffA);
.LBB0_177:
	ds_read_b128 v[128:131], v183
	ds_read_b128 v[132:135], v183 offset:1024
	ds_read_b128 v[136:139], v183 offset:2048
	ds_read_b128 v[140:143], v183 offset:3072
	ds_read_b128 v[166:169], v184
	ds_read_b128 v[170:173], v184 offset:1024
	ds_read_b128 v[188:191], v184 offset:2048
	ds_read_b128 v[196:199], v184 offset:3072
	s_add_u32 s12, s10, 0xfff80080
	s_addc_u32 s13, s11, -1
	s_cmp_eq_u32 s55, 28
	s_cselect_b32 s59, s0, s13
	s_cselect_b32 s58, s2, s12
	s_cselect_b32 s13, s3, s33
	s_cselect_b32 s12, s7, s9
	v_lshl_add_u64 v[192:193], s[10:11], 0, v[158:159]
	s_add_i32 m0, s74, 0xc000
	ds_read_b128 v[200:203], v185
	ds_read_b128 v[204:207], v185 offset:1024
	ds_read_b128 v[208:211], v185 offset:2048
	ds_read_b128 v[212:215], v185 offset:3072
	ds_read_b128 v[216:219], v185 offset:4096
	ds_read_b128 v[220:223], v185 offset:5120
	ds_read_b128 v[224:227], v185 offset:6144
	ds_read_b128 v[228:231], v185 offset:7168
	global_load_lds_dwordx4 v[192:193], off
	v_lshl_add_u64 v[192:193], s[10:11], 0, v[160:161]
	s_add_i32 m0, s74, 0xe000
	s_nop 0
	global_load_lds_dwordx4 v[192:193], off
	s_waitcnt vmcnt(8)
	s_waitcnt lgkmcnt(0)
	s_barrier
	s_setprio 1
	s_waitcnt lgkmcnt(0)
	v_mfma_f32_16x16x32_bf16 v[124:127], v[128:131], v[200:203], v[124:127]
	v_mfma_f32_16x16x32_bf16 v[120:123], v[136:139], v[200:203], v[120:123]
	v_mfma_f32_16x16x32_bf16 v[116:119], v[128:131], v[208:211], v[116:119]
	v_mfma_f32_16x16x32_bf16 v[112:115], v[136:139], v[208:211], v[112:115]
	v_mfma_f32_16x16x32_bf16 v[100:103], v[128:131], v[216:219], v[100:103]
	v_mfma_f32_16x16x32_bf16 v[96:99], v[136:139], v[216:219], v[96:99]
	v_mfma_f32_16x16x32_bf16 v[84:87], v[128:131], v[224:227], v[84:87]
	v_mfma_f32_16x16x32_bf16 v[80:83], v[136:139], v[224:227], v[80:83]
	v_mfma_f32_16x16x32_bf16 v[124:127], v[132:135], v[204:207], v[124:127]
	v_mfma_f32_16x16x32_bf16 v[120:123], v[140:143], v[204:207], v[120:123]
	v_mfma_f32_16x16x32_bf16 v[116:119], v[132:135], v[212:215], v[116:119]
	v_mfma_f32_16x16x32_bf16 v[112:115], v[140:143], v[212:215], v[112:115]
	v_mfma_f32_16x16x32_bf16 v[100:103], v[132:135], v[220:223], v[100:103]
	v_mfma_f32_16x16x32_bf16 v[96:99], v[140:143], v[220:223], v[96:99]
	v_mfma_f32_16x16x32_bf16 v[84:87], v[132:135], v[228:231], v[84:87]
	v_mfma_f32_16x16x32_bf16 v[80:83], v[140:143], v[228:231], v[80:83]
	v_mfma_f32_16x16x32_bf16 v[108:111], v[166:169], v[200:203], v[108:111]
	v_mfma_f32_16x16x32_bf16 v[104:107], v[188:191], v[200:203], v[104:107]
	v_mfma_f32_16x16x32_bf16 v[92:95], v[166:169], v[208:211], v[92:95]
	v_mfma_f32_16x16x32_bf16 v[88:91], v[188:191], v[208:211], v[88:91]
	v_mfma_f32_16x16x32_bf16 v[76:79], v[166:169], v[216:219], v[76:79]
	v_mfma_f32_16x16x32_bf16 v[72:75], v[188:191], v[216:219], v[72:75]
	v_mfma_f32_16x16x32_bf16 v[68:71], v[166:169], v[224:227], v[68:71]
	v_mfma_f32_16x16x32_bf16 v[64:67], v[188:191], v[224:227], v[64:67]
	v_mfma_f32_16x16x32_bf16 v[108:111], v[170:173], v[204:207], v[108:111]
	v_mfma_f32_16x16x32_bf16 v[104:107], v[196:199], v[204:207], v[104:107]
	v_mfma_f32_16x16x32_bf16 v[92:95], v[170:173], v[212:215], v[92:95]
	v_mfma_f32_16x16x32_bf16 v[88:91], v[196:199], v[212:215], v[88:91]
	v_mfma_f32_16x16x32_bf16 v[76:79], v[170:173], v[220:223], v[76:79]
	v_mfma_f32_16x16x32_bf16 v[72:75], v[196:199], v[220:223], v[72:75]
	v_mfma_f32_16x16x32_bf16 v[68:71], v[170:173], v[228:231], v[68:71]
	v_mfma_f32_16x16x32_bf16 v[64:67], v[196:199], v[228:231], v[64:67]
	s_setprio 0
	s_barrier
	s_add_i32 s57, s82, s73
	v_lshl_add_u64 v[192:193], s[12:13], 0, v[146:147]
	s_mov_b32 m0, s57
	ds_read_b128 v[200:203], v185 offset:16384
	ds_read_b128 v[204:207], v185 offset:17408
	ds_read_b128 v[208:211], v185 offset:18432
	ds_read_b128 v[212:215], v185 offset:19456
	ds_read_b128 v[216:219], v185 offset:20480
	ds_read_b128 v[220:223], v185 offset:21504
	ds_read_b128 v[224:227], v185 offset:22528
	ds_read_b128 v[228:231], v185 offset:23552
	global_load_lds_dwordx4 v[192:193], off
	s_add_i32 m0, s57, 0x2000
	s_add_u32 s66, s12, 0x80000
	v_lshl_add_u64 v[232:233], s[12:13], 0, v[150:151]
	s_addc_u32 s67, s13, 0
	s_add_i32 s57, s83, s73
	global_load_lds_dwordx4 v[232:233], off
	v_lshl_add_u64 v[234:235], s[66:67], 0, v[146:147]
	s_mov_b32 m0, s57
	v_lshl_add_u64 v[236:237], s[58:59], 0, v[148:149]
	global_load_lds_dwordx4 v[234:235], off
	v_lshl_add_u64 v[234:235], s[66:67], 0, v[150:151]
	s_add_i32 m0, s57, 0x2000
	s_nop 0
	global_load_lds_dwordx4 v[234:235], off
	v_lshl_add_u64 v[234:235], s[58:59], 0, v[144:145]
	s_mov_b32 m0, s74
	s_nop 0
	global_load_lds_dwordx4 v[234:235], off
	s_mov_b32 m0, s75
	s_nop 0
	global_load_lds_dwordx4 v[236:237], off
	s_waitcnt vmcnt(8)
	s_waitcnt lgkmcnt(0)
	s_barrier
; #define PG8_STAGE(bufoff, gbase, voff) do { _Pragma("unroll") for (int _i = 0; _i < 2; ++_i) \
;         __builtin_amdgcn_global_load_lds((const unsigned*)((const char*)(gbase) + (voff)[_i]), (PG8_LAS unsigned*)(lds + (bufoff) + ldsw + _i * 8192), 16, 0, 0); } while (0)
; #define PG8_LDA(dst, b, h) do { _Pragma("unroll") for (int m = 0; m < 4; ++m) _Pragma("unroll") for (int k = 0; k < 2; ++k) dst[m][k] = *(const PG8_LAS bf16x8*)(lds + PG8_SA(b, h) + aoff + m * 2048 + k * 1024); } while (0)
; #define PG8_LDB(dst, b, h) do { _Pragma("unroll") for (int n = 0; n < 2; ++n) _Pragma("unroll") for (int k = 0; k < 2; ++k) dst[n][k] = *(const PG8_LAS bf16x8*)(lds + PG8_SB(b, h) + boff + n * 2048 + k * 1024); } while (0)
; #define PG8_MMA(ai, bj, At, Bt) do { __builtin_amdgcn_s_setprio(1); _Pragma("unroll") for (int m = 0; m < 4; ++m) _Pragma("unroll") for (int n = 0; n < 2; ++n) _Pragma("unroll") for (int k = 0; k < 2; ++k) \
;         acc[ai][bj][m][n] = __builtin_amdgcn_mfma_f32_16x16x32_bf16(Bt[n][k], At[m][k], acc[ai][bj][m][n], 0, 0, 0); __builtin_amdgcn_s_setprio(0); } while (0)
; #define PG8_WAIT_V(n) asm volatile("s_waitcnt vmcnt(" #n ")" ::: "memory")
; #define PG8_WAIT_L(n) asm volatile("s_waitcnt lgkmcnt(" #n ")" ::: "memory")
; #define PG8_BAR __builtin_amdgcn_s_barrier()
; #define PG8_SCHED __builtin_amdgcn_sched_barrier(0)
; template <class Epi, class Sched, bool ALIGN_EPI = false, bool SP2 = false>
; __device__ __forceinline__ void gemm_phase(PG8_LAS unsigned char* lds, const Gemm g, const Sched& S, const Epi& E) {
;     ...
;             PG8_WAIT_V(8); PG8_WAIT_L(0); PG8_BAR; PG8_MMA(1, 0, At, B0); PG8_MMA(1, 1, At, B1); PG8_BAR; PG8_SCHED;
;             PG8_LDB(B0, 1, 0); PG8_LDB(B1, 1, 1); PG8_SCHED; PG8_LDA(At, 1, 0); PG8_STAGE(PG8_SA(0, 1), a2 + hstepA, voffA);
;             PG8_WAIT_V(8); PG8_WAIT_L(0); PG8_BAR; PG8_MMA(0, 0, At, B0); PG8_MMA(0, 1, At, B1); PG8_BAR; PG8_SCHED;
	s_setprio 1
	s_waitcnt lgkmcnt(0)
	v_mfma_f32_16x16x32_bf16 v[60:63], v[128:131], v[200:203], v[60:63]
	v_mfma_f32_16x16x32_bf16 v[56:59], v[136:139], v[200:203], v[56:59]
	v_mfma_f32_16x16x32_bf16 v[52:55], v[128:131], v[208:211], v[52:55]
	v_mfma_f32_16x16x32_bf16 v[48:51], v[136:139], v[208:211], v[48:51]
	v_mfma_f32_16x16x32_bf16 v[36:39], v[128:131], v[216:219], v[36:39]
	v_mfma_f32_16x16x32_bf16 v[32:35], v[136:139], v[216:219], v[32:35]
	v_mfma_f32_16x16x32_bf16 v[20:23], v[128:131], v[224:227], v[20:23]
	v_mfma_f32_16x16x32_bf16 v[16:19], v[136:139], v[224:227], v[16:19]
	v_mfma_f32_16x16x32_bf16 v[60:63], v[132:135], v[204:207], v[60:63]
	v_mfma_f32_16x16x32_bf16 v[56:59], v[140:143], v[204:207], v[56:59]
	v_mfma_f32_16x16x32_bf16 v[52:55], v[132:135], v[212:215], v[52:55]
	v_mfma_f32_16x16x32_bf16 v[48:51], v[140:143], v[212:215], v[48:51]
	v_mfma_f32_16x16x32_bf16 v[36:39], v[132:135], v[220:223], v[36:39]
	v_mfma_f32_16x16x32_bf16 v[32:35], v[140:143], v[220:223], v[32:35]
	v_mfma_f32_16x16x32_bf16 v[20:23], v[132:135], v[228:231], v[20:23]
	v_mfma_f32_16x16x32_bf16 v[16:19], v[140:143], v[228:231], v[16:19]
	v_mfma_f32_16x16x32_bf16 v[44:47], v[166:169], v[200:203], v[44:47]
	v_mfma_f32_16x16x32_bf16 v[40:43], v[188:191], v[200:203], v[40:43]
	v_mfma_f32_16x16x32_bf16 v[28:31], v[166:169], v[208:211], v[28:31]
	v_mfma_f32_16x16x32_bf16 v[24:27], v[188:191], v[208:211], v[24:27]
	v_mfma_f32_16x16x32_bf16 v[12:15], v[166:169], v[216:219], v[12:15]
	v_mfma_f32_16x16x32_bf16 v[8:11], v[188:191], v[216:219], v[8:11]
	v_mfma_f32_16x16x32_bf16 v[4:7], v[166:169], v[224:227], v[4:7]
	v_mfma_f32_16x16x32_bf16 v[0:3], v[188:191], v[224:227], v[0:3]
	v_mfma_f32_16x16x32_bf16 v[44:47], v[170:173], v[204:207], v[44:47]
	v_mfma_f32_16x16x32_bf16 v[40:43], v[196:199], v[204:207], v[40:43]
	v_mfma_f32_16x16x32_bf16 v[28:31], v[170:173], v[212:215], v[28:31]
	v_mfma_f32_16x16x32_bf16 v[24:27], v[196:199], v[212:215], v[24:27]
	v_mfma_f32_16x16x32_bf16 v[12:15], v[170:173], v[220:223], v[12:15]
	v_mfma_f32_16x16x32_bf16 v[8:11], v[196:199], v[220:223], v[8:11]
	v_mfma_f32_16x16x32_bf16 v[4:7], v[170:173], v[228:231], v[4:7]
	v_mfma_f32_16x16x32_bf16 v[0:3], v[196:199], v[228:231], v[0:3]
	s_setprio 0
	s_barrier
	s_add_i32 s57, 0, 0x18000
	s_add_i32 s66, 0, 0x1c000
	v_add_u32_e32 v140, s57, v177
	v_add_u32_e32 v152, s66, v177
	ds_read_b128 v[128:131], v140
	ds_read_b128 v[132:135], v140 offset:1024
	ds_read_b128 v[136:139], v140 offset:2048
	ds_read_b128 v[140:143], v140 offset:3072
	ds_read_b128 v[166:169], v152
	ds_read_b128 v[170:173], v152 offset:1024
	ds_read_b128 v[188:191], v152 offset:2048
	ds_read_b128 v[196:199], v152 offset:3072
	s_add_u32 s58, s58, 0x80000
	s_addc_u32 s59, s59, 0
	s_mov_b32 m0, s76
	v_lshl_add_u64 v[238:239], s[58:59], 0, v[144:145]
	ds_read_b128 v[200:203], v185 offset:32768
	ds_read_b128 v[204:207], v185 offset:33792
	ds_read_b128 v[208:211], v185 offset:34816
	ds_read_b128 v[212:215], v185 offset:35840
	ds_read_b128 v[216:219], v185 offset:36864
	ds_read_b128 v[220:223], v185 offset:37888
	ds_read_b128 v[224:227], v185 offset:38912
	ds_read_b128 v[228:231], v185 offset:39936
	global_load_lds_dwordx4 v[238:239], off
	v_lshl_add_u64 v[238:239], s[58:59], 0, v[148:149]
	s_mov_b32 m0, s77
	s_nop 0
	global_load_lds_dwordx4 v[238:239], off
	s_waitcnt vmcnt(8)
	s_waitcnt lgkmcnt(0)
	s_barrier
	s_setprio 1
	s_waitcnt lgkmcnt(0)
	v_mfma_f32_16x16x32_bf16 v[124:127], v[128:131], v[200:203], v[124:127]
	v_mfma_f32_16x16x32_bf16 v[120:123], v[136:139], v[200:203], v[120:123]
	v_mfma_f32_16x16x32_bf16 v[116:119], v[128:131], v[208:211], v[116:119]
	v_mfma_f32_16x16x32_bf16 v[112:115], v[136:139], v[208:211], v[112:115]
	v_mfma_f32_16x16x32_bf16 v[100:103], v[128:131], v[216:219], v[100:103]
	v_mfma_f32_16x16x32_bf16 v[96:99], v[136:139], v[216:219], v[96:99]
	v_mfma_f32_16x16x32_bf16 v[84:87], v[128:131], v[224:227], v[84:87]
	v_mfma_f32_16x16x32_bf16 v[80:83], v[136:139], v[224:227], v[80:83]
	v_mfma_f32_16x16x32_bf16 v[124:127], v[132:135], v[204:207], v[124:127]
	v_mfma_f32_16x16x32_bf16 v[120:123], v[140:143], v[204:207], v[120:123]
	v_mfma_f32_16x16x32_bf16 v[116:119], v[132:135], v[212:215], v[116:119]
	v_mfma_f32_16x16x32_bf16 v[112:115], v[140:143], v[212:215], v[112:115]
	v_mfma_f32_16x16x32_bf16 v[100:103], v[132:135], v[220:223], v[100:103]
	v_mfma_f32_16x16x32_bf16 v[96:99], v[140:143], v[220:223], v[96:99]
	v_mfma_f32_16x16x32_bf16 v[84:87], v[132:135], v[228:231], v[84:87]
	v_mfma_f32_16x16x32_bf16 v[80:83], v[140:143], v[228:231], v[80:83]
	v_mfma_f32_16x16x32_bf16 v[108:111], v[166:169], v[200:203], v[108:111]
	v_mfma_f32_16x16x32_bf16 v[104:107], v[188:191], v[200:203], v[104:107]
	v_mfma_f32_16x16x32_bf16 v[92:95], v[166:169], v[208:211], v[92:95]
	v_mfma_f32_16x16x32_bf16 v[88:91], v[188:191], v[208:211], v[88:91]
	v_mfma_f32_16x16x32_bf16 v[76:79], v[166:169], v[216:219], v[76:79]
	v_mfma_f32_16x16x32_bf16 v[72:75], v[188:191], v[216:219], v[72:75]
	v_mfma_f32_16x16x32_bf16 v[68:71], v[166:169], v[224:227], v[68:71]
	v_mfma_f32_16x16x32_bf16 v[64:67], v[188:191], v[224:227], v[64:67]
	v_mfma_f32_16x16x32_bf16 v[108:111], v[170:173], v[204:207], v[108:111]
	v_mfma_f32_16x16x32_bf16 v[104:107], v[196:199], v[204:207], v[104:107]
	v_mfma_f32_16x16x32_bf16 v[92:95], v[170:173], v[212:215], v[92:95]
	v_mfma_f32_16x16x32_bf16 v[88:91], v[196:199], v[212:215], v[88:91]
	v_mfma_f32_16x16x32_bf16 v[76:79], v[170:173], v[220:223], v[76:79]
	v_mfma_f32_16x16x32_bf16 v[72:75], v[196:199], v[220:223], v[72:75]
	v_mfma_f32_16x16x32_bf16 v[68:71], v[170:173], v[228:231], v[68:71]
	v_mfma_f32_16x16x32_bf16 v[64:67], v[196:199], v[228:231], v[64:67]
	s_setprio 0
	s_barrier
; #define PG8_STAGE(bufoff, gbase, voff) do { _Pragma("unroll") for (int _i = 0; _i < 2; ++_i) \
;         __builtin_amdgcn_global_load_lds((const unsigned*)((const char*)(gbase) + (voff)[_i]), (PG8_LAS unsigned*)(lds + (bufoff) + ldsw + _i * 8192), 16, 0, 0); } while (0)
; #define PG8_LDA(dst, b, h) do { _Pragma("unroll") for (int m = 0; m < 4; ++m) _Pragma("unroll") for (int k = 0; k < 2; ++k) dst[m][k] = *(const PG8_LAS bf16x8*)(lds + PG8_SA(b, h) + aoff + m * 2048 + k * 1024); } while (0)
; #define PG8_WAIT_V(n) asm volatile("s_waitcnt vmcnt(" #n ")" ::: "memory")
; #define PG8_WAIT_L(n) asm volatile("s_waitcnt lgkmcnt(" #n ")" ::: "memory")
; template <class Epi, class Sched, bool ALIGN_EPI = false, bool SP2 = false>
; __device__ __forceinline__ void gemm_phase(PG8_LAS unsigned char* lds, const Gemm g, const Sched& S, const Epi& E) {
;     ...
;         for (int t = 0; t < nt; t += 2) {
;             const bool last = (t == nt - 2);
;             const char* a1 = cA + (size_t)(t + 1) * kstep;
;             const char* a2 = last ? nA : cA + (size_t)(t + 2) * kstep; const char* b2 = last ? nB : cB + (size_t)(t + 2) * kstep;
;             const char* a3 = a2 + kstep; const char* b3 = b2 + kstep;
;             if (last && has_next) S.a_ready(nxt);
;             if constexpr (SP2) {
;             PG8_LDB(B0, 0, 0); PG8_LDB(B1, 0, 1); PG8_SCHED; PG8_LDA(At, 0, 0); PG8_STAGE(PG8_SA(1, 1), a1 + hstepA, voffA);
;             PG8_WAIT_V(8); PG8_WAIT_L(0); PG8_BAR; PG8_MMA(0, 0, At, B0); PG8_MMA(0, 1, At, B1); PG8_BAR; PG8_SCHED;
;             PG8_LDA(At, 0, 1); PG8_STAGE(PG8_SB(0, 0), b2, voffB); PG8_STAGE(PG8_SB(0, 1), b2 + hstepB, voffB); PG8_STAGE(PG8_SA(0, 0), a2, voffA);
;             PG8_WAIT_V(8); PG8_WAIT_L(0); PG8_BAR; PG8_MMA(1, 0, At, B0); PG8_MMA(1, 1, At, B1); PG8_BAR; PG8_SCHED;
;             PG8_LDB(B0, 1, 0); PG8_LDB(B1, 1, 1); PG8_SCHED; PG8_LDA(At, 1, 0); PG8_STAGE(PG8_SA(0, 1), a2 + hstepA, voffA);
;             PG8_WAIT_V(8); PG8_WAIT_L(0); PG8_BAR; PG8_MMA(0, 0, At, B0); PG8_MMA(0, 1, At, B1); PG8_BAR; PG8_SCHED;
;             PG8_LDA(At, 1, 1); PG8_STAGE(PG8_SB(1, 0), b3, voffB); PG8_STAGE(PG8_SB(1, 1), b3 + hstepB, voffB); PG8_STAGE(PG8_SA(1, 0), a3, voffA);
;             PG8_WAIT_V(8); PG8_WAIT_L(0); PG8_BAR; PG8_MMA(1, 0, At, B0); PG8_MMA(1, 1, At, B1); PG8_BAR; PG8_SCHED;
;     ...
;         if constexpr (ALIGN_EPI) { if (wr == 0) PG8_BAR; }
	s_add_i32 s57, s57, s73
	v_lshl_add_u64 v[192:193], v[192:193], 0, s[42:43]
	s_mov_b32 m0, s57
	ds_read_b128 v[200:203], v185 offset:49152
	ds_read_b128 v[204:207], v185 offset:50176
	ds_read_b128 v[208:211], v185 offset:51200
	ds_read_b128 v[212:215], v185 offset:52224
	ds_read_b128 v[216:219], v185 offset:53248
	ds_read_b128 v[220:223], v185 offset:54272
	ds_read_b128 v[224:227], v185 offset:55296
	ds_read_b128 v[228:231], v185 offset:56320
	global_load_lds_dwordx4 v[192:193], off
	s_add_i32 m0, s57, 0x2000
	s_add_u32 s12, s12, 0x80080
	v_lshl_add_u64 v[192:193], v[232:233], 0, s[42:43]
	s_addc_u32 s13, s13, 0
	s_add_i32 s57, s66, s73
	global_load_lds_dwordx4 v[192:193], off
	v_lshl_add_u64 v[192:193], s[12:13], 0, v[146:147]
	s_mov_b32 m0, s57
	s_nop 0
	global_load_lds_dwordx4 v[192:193], off
	v_lshl_add_u64 v[192:193], s[12:13], 0, v[150:151]
	s_add_i32 m0, s57, 0x2000
	s_nop 0
	global_load_lds_dwordx4 v[192:193], off
	v_lshl_add_u64 v[192:193], v[234:235], 0, s[42:43]
	s_mov_b32 m0, s80
	s_nop 0
	global_load_lds_dwordx4 v[192:193], off
	v_lshl_add_u64 v[192:193], v[236:237], 0, s[42:43]
	s_mov_b32 m0, s81
	s_nop 0
	global_load_lds_dwordx4 v[192:193], off
	s_waitcnt vmcnt(8)
	s_waitcnt lgkmcnt(0)
	s_barrier
	s_setprio 1
	s_waitcnt lgkmcnt(0)
	v_mfma_f32_16x16x32_bf16 v[60:63], v[128:131], v[200:203], v[60:63]
	v_mfma_f32_16x16x32_bf16 v[56:59], v[136:139], v[200:203], v[56:59]
	v_mfma_f32_16x16x32_bf16 v[52:55], v[128:131], v[208:211], v[52:55]
	v_mfma_f32_16x16x32_bf16 v[48:51], v[136:139], v[208:211], v[48:51]
	v_mfma_f32_16x16x32_bf16 v[36:39], v[128:131], v[216:219], v[36:39]
	v_mfma_f32_16x16x32_bf16 v[32:35], v[136:139], v[216:219], v[32:35]
	v_mfma_f32_16x16x32_bf16 v[20:23], v[128:131], v[224:227], v[20:23]
	v_mfma_f32_16x16x32_bf16 v[16:19], v[136:139], v[224:227], v[16:19]
	v_mfma_f32_16x16x32_bf16 v[60:63], v[132:135], v[204:207], v[60:63]
	v_mfma_f32_16x16x32_bf16 v[56:59], v[140:143], v[204:207], v[56:59]
	v_mfma_f32_16x16x32_bf16 v[52:55], v[132:135], v[212:215], v[52:55]
	v_mfma_f32_16x16x32_bf16 v[48:51], v[140:143], v[212:215], v[48:51]
	v_mfma_f32_16x16x32_bf16 v[36:39], v[132:135], v[220:223], v[36:39]
	v_mfma_f32_16x16x32_bf16 v[32:35], v[140:143], v[220:223], v[32:35]
	v_mfma_f32_16x16x32_bf16 v[20:23], v[132:135], v[228:231], v[20:23]
	v_mfma_f32_16x16x32_bf16 v[16:19], v[140:143], v[228:231], v[16:19]
	v_mfma_f32_16x16x32_bf16 v[44:47], v[166:169], v[200:203], v[44:47]
	v_mfma_f32_16x16x32_bf16 v[40:43], v[188:191], v[200:203], v[40:43]
	v_mfma_f32_16x16x32_bf16 v[28:31], v[166:169], v[208:211], v[28:31]
	v_mfma_f32_16x16x32_bf16 v[24:27], v[188:191], v[208:211], v[24:27]
	v_mfma_f32_16x16x32_bf16 v[12:15], v[166:169], v[216:219], v[12:15]
	v_mfma_f32_16x16x32_bf16 v[8:11], v[188:191], v[216:219], v[8:11]
	v_mfma_f32_16x16x32_bf16 v[4:7], v[166:169], v[224:227], v[4:7]
	v_mfma_f32_16x16x32_bf16 v[0:3], v[188:191], v[224:227], v[0:3]
	v_mfma_f32_16x16x32_bf16 v[44:47], v[170:173], v[204:207], v[44:47]
	v_mfma_f32_16x16x32_bf16 v[40:43], v[196:199], v[204:207], v[40:43]
	v_mfma_f32_16x16x32_bf16 v[28:31], v[170:173], v[212:215], v[28:31]
	v_mfma_f32_16x16x32_bf16 v[24:27], v[196:199], v[212:215], v[24:27]
	v_mfma_f32_16x16x32_bf16 v[12:15], v[170:173], v[220:223], v[12:15]
	v_mfma_f32_16x16x32_bf16 v[8:11], v[196:199], v[220:223], v[8:11]
	v_mfma_f32_16x16x32_bf16 v[4:7], v[170:173], v[228:231], v[4:7]
	v_mfma_f32_16x16x32_bf16 v[0:3], v[196:199], v[228:231], v[0:3]
	s_setprio 0
	s_barrier
	s_add_i32 s55, s55, 2
	s_add_u32 s10, s10, 0x100
	s_addc_u32 s11, s11, 0
	s_add_u32 s9, s9, 0x100
	s_addc_u32 s33, s33, 0
	s_cmp_gt_u32 s55, 29
	s_cbranch_scc0 .LBB0_177
	s_and_b64 vcc, exec, s[44:45]
	s_cbranch_vccz .LBB0_180
	s_barrier

; #define PG8_STAGE(bufoff, gbase, voff) do { _Pragma("unroll") for (int _i = 0; _i < 2; ++_i) \
;         __builtin_amdgcn_global_load_lds((const unsigned*)((const char*)(gbase) + (voff)[_i]), (PG8_LAS unsigned*)(lds + (bufoff) + ldsw + _i * 8192), 16, 0, 0); } while (0)
; #define PG8_LDA(dst, b, h) do { _Pragma("unroll") for (int m = 0; m < 4; ++m) _Pragma("unroll") for (int k = 0; k < 2; ++k) dst[m][k] = *(const PG8_LAS bf16x8*)(lds + PG8_SA(b, h) + aoff + m * 2048 + k * 1024); } while (0)
; #define PG8_LDB(dst, b, h) do { _Pragma("unroll") for (int n = 0; n < 2; ++n) _Pragma("unroll") for (int k = 0; k < 2; ++k) dst[n][k] = *(const PG8_LAS bf16x8*)(lds + PG8_SB(b, h) + boff + n * 2048 + k * 1024); } while (0)
; #define PG8_MMA(ai, bj, At, Bt) do { __builtin_amdgcn_s_setprio(1); _Pragma("unroll") for (int m = 0; m < 4; ++m) _Pragma("unroll") for (int n = 0; n < 2; ++n) _Pragma("unroll") for (int k = 0; k < 2; ++k) \
;         acc[ai][bj][m][n] = __builtin_amdgcn_mfma_f32_16x16x32_bf16(Bt[n][k], At[m][k], acc[ai][bj][m][n], 0, 0, 0); __builtin_amdgcn_s_setprio(0); } while (0)
; #define PG8_WAIT_V(n) asm volatile("s_waitcnt vmcnt(" #n ")" ::: "memory")
; #define PG8_WAIT_L(n) asm volatile("s_waitcnt lgkmcnt(" #n ")" ::: "memory")
; #define PG8_BAR __builtin_amdgcn_s_barrier()
; #define PG8_SCHED __builtin_amdgcn_sched_barrier(0)
; template <class Epi, class Sched, bool ALIGN_EPI = false, bool SP2 = false>
; __device__ __forceinline__ void gemm_phase(PG8_LAS unsigned char* lds, const Gemm g, const Sched& S, const Epi& E) {
;     ...
;             const bool last = (t == nt - 2);
;             const char* a1 = cA + (size_t)(t + 1) * kstep;
;             const char* a2 = last ? nA : cA + (size_t)(t + 2) * kstep; const char* b2 = last ? nB : cB + (size_t)(t + 2) * kstep;
;             const char* a3 = a2 + kstep; const char* b3 = b2 + kstep;
;             if (last && has_next) S.a_ready(nxt);
;             if constexpr (SP2) {
;             PG8_LDB(B0, 0, 0); PG8_LDB(B1, 0, 1); PG8_SCHED; PG8_LDA(At, 0, 0); PG8_STAGE(PG8_SA(1, 1), a1 + hstepA, voffA);
;             PG8_WAIT_V(8); PG8_WAIT_L(0); PG8_BAR; PG8_MMA(0, 0, At, B0); PG8_MMA(0, 1, At, B1); PG8_BAR; PG8_SCHED;
;             PG8_LDA(At, 0, 1); PG8_STAGE(PG8_SB(0, 0), b2, voffB); PG8_STAGE(PG8_SB(0, 1), b2 + hstepB, voffB); PG8_STAGE(PG8_SA(0, 0), a2, voffA);
.LBB0_521:
	ds_read_b128 v[144:147], v151
	ds_read_b128 v[154:157], v151 offset:1024
	ds_read_b128 v[158:161], v151 offset:2048
	ds_read_b128 v[170:173], v151 offset:3072
	ds_read_b128 v[174:177], v152
	ds_read_b128 v[178:181], v152 offset:1024
	ds_read_b128 v[182:185], v152 offset:2048
	ds_read_b128 v[186:189], v152 offset:3072
	s_add_u32 s36, s34, 0xfffc0080
	s_addc_u32 s37, s35, -1
	s_cmp_eq_u32 s52, 12
	s_cselect_b32 s39, s25, s37
	s_cselect_b32 s38, s48, s36
	s_cselect_b32 s37, s23, s51
	s_cselect_b32 s36, s49, s50
	v_lshl_add_u64 v[224:225], s[34:35], 0, v[136:137]
	s_add_i32 m0, s31, 0xc000
	ds_read_b128 v[190:193], v153
	ds_read_b128 v[196:199], v153 offset:1024
	ds_read_b128 v[200:203], v153 offset:2048
	ds_read_b128 v[204:207], v153 offset:3072
	ds_read_b128 v[208:211], v153 offset:4096
	ds_read_b128 v[212:215], v153 offset:5120
	ds_read_b128 v[216:219], v153 offset:6144
	ds_read_b128 v[220:223], v153 offset:7168
	global_load_lds_dwordx4 v[224:225], off
	v_lshl_add_u64 v[224:225], s[34:35], 0, v[138:139]
	s_add_i32 m0, s31, 0xe000
	s_nop 0
	global_load_lds_dwordx4 v[224:225], off
	s_waitcnt vmcnt(8)
	s_waitcnt lgkmcnt(0)
	s_barrier
	s_setprio 1
	s_waitcnt lgkmcnt(0)
	v_mfma_f32_16x16x32_bf16 v[124:127], v[144:147], v[190:193], v[124:127]
	v_mfma_f32_16x16x32_bf16 v[120:123], v[158:161], v[190:193], v[120:123]
	v_mfma_f32_16x16x32_bf16 v[108:111], v[144:147], v[200:203], v[108:111]
	v_mfma_f32_16x16x32_bf16 v[104:107], v[158:161], v[200:203], v[104:107]
	v_mfma_f32_16x16x32_bf16 v[92:95], v[144:147], v[208:211], v[92:95]
	v_mfma_f32_16x16x32_bf16 v[88:91], v[158:161], v[208:211], v[88:91]
	v_mfma_f32_16x16x32_bf16 v[76:79], v[144:147], v[216:219], v[76:79]
	v_mfma_f32_16x16x32_bf16 v[72:75], v[158:161], v[216:219], v[72:75]
	v_mfma_f32_16x16x32_bf16 v[124:127], v[154:157], v[196:199], v[124:127]
	v_mfma_f32_16x16x32_bf16 v[120:123], v[170:173], v[196:199], v[120:123]
	v_mfma_f32_16x16x32_bf16 v[108:111], v[154:157], v[204:207], v[108:111]
	v_mfma_f32_16x16x32_bf16 v[104:107], v[170:173], v[204:207], v[104:107]
	v_mfma_f32_16x16x32_bf16 v[92:95], v[154:157], v[212:215], v[92:95]
	v_mfma_f32_16x16x32_bf16 v[88:91], v[170:173], v[212:215], v[88:91]
	v_mfma_f32_16x16x32_bf16 v[76:79], v[154:157], v[220:223], v[76:79]
	v_mfma_f32_16x16x32_bf16 v[72:75], v[170:173], v[220:223], v[72:75]
	v_mfma_f32_16x16x32_bf16 v[116:119], v[174:177], v[190:193], v[116:119]
	v_mfma_f32_16x16x32_bf16 v[112:115], v[182:185], v[190:193], v[112:115]
	v_mfma_f32_16x16x32_bf16 v[100:103], v[174:177], v[200:203], v[100:103]
	v_mfma_f32_16x16x32_bf16 v[96:99], v[182:185], v[200:203], v[96:99]
	v_mfma_f32_16x16x32_bf16 v[84:87], v[174:177], v[208:211], v[84:87]
	v_mfma_f32_16x16x32_bf16 v[80:83], v[182:185], v[208:211], v[80:83]
	v_mfma_f32_16x16x32_bf16 v[68:71], v[174:177], v[216:219], v[68:71]
	v_mfma_f32_16x16x32_bf16 v[64:67], v[182:185], v[216:219], v[64:67]
	v_mfma_f32_16x16x32_bf16 v[116:119], v[178:181], v[196:199], v[116:119]
	v_mfma_f32_16x16x32_bf16 v[112:115], v[186:189], v[196:199], v[112:115]
	v_mfma_f32_16x16x32_bf16 v[100:103], v[178:181], v[204:207], v[100:103]
	v_mfma_f32_16x16x32_bf16 v[96:99], v[186:189], v[204:207], v[96:99]
	v_mfma_f32_16x16x32_bf16 v[84:87], v[178:181], v[212:215], v[84:87]
	v_mfma_f32_16x16x32_bf16 v[80:83], v[186:189], v[212:215], v[80:83]
	v_mfma_f32_16x16x32_bf16 v[68:71], v[178:181], v[220:223], v[68:71]
	v_mfma_f32_16x16x32_bf16 v[64:67], v[186:189], v[220:223], v[64:67]
	s_setprio 0
	s_barrier
	s_add_i32 s53, s56, s33
	v_lshl_add_u64 v[224:225], s[36:37], 0, v[132:133]
	s_mov_b32 m0, s53
	ds_read_b128 v[190:193], v153 offset:16384
	ds_read_b128 v[196:199], v153 offset:17408
	ds_read_b128 v[200:203], v153 offset:18432
	ds_read_b128 v[204:207], v153 offset:19456
	ds_read_b128 v[208:211], v153 offset:20480
	ds_read_b128 v[212:215], v153 offset:21504
	ds_read_b128 v[216:219], v153 offset:22528
	ds_read_b128 v[220:223], v153 offset:23552
	global_load_lds_dwordx4 v[224:225], off
	s_add_i32 m0, s53, 0x2000
	s_add_u32 s54, s36, 0x40000
	v_lshl_add_u64 v[226:227], s[36:37], 0, v[128:129]
	s_addc_u32 s55, s37, 0
	s_add_i32 s53, s46, s33
	global_load_lds_dwordx4 v[226:227], off
	v_lshl_add_u64 v[228:229], s[54:55], 0, v[132:133]
	s_mov_b32 m0, s53
	v_lshl_add_u64 v[230:231], s[38:39], 0, v[130:131]
	global_load_lds_dwordx4 v[228:229], off
	v_lshl_add_u64 v[228:229], s[54:55], 0, v[128:129]
	s_add_i32 m0, s53, 0x2000
	s_nop 0
	global_load_lds_dwordx4 v[228:229], off
	v_lshl_add_u64 v[228:229], s[38:39], 0, v[134:135]
	s_mov_b32 m0, s31
	s_nop 0
	global_load_lds_dwordx4 v[228:229], off
	s_mov_b32 m0, s40
	s_nop 0
	global_load_lds_dwordx4 v[230:231], off
	s_waitcnt vmcnt(8)
	s_waitcnt lgkmcnt(0)
	s_barrier
; #define PG8_STAGE(bufoff, gbase, voff) do { _Pragma("unroll") for (int _i = 0; _i < 2; ++_i) \
;         __builtin_amdgcn_global_load_lds((const unsigned*)((const char*)(gbase) + (voff)[_i]), (PG8_LAS unsigned*)(lds + (bufoff) + ldsw + _i * 8192), 16, 0, 0); } while (0)
; #define PG8_LDA(dst, b, h) do { _Pragma("unroll") for (int m = 0; m < 4; ++m) _Pragma("unroll") for (int k = 0; k < 2; ++k) dst[m][k] = *(const PG8_LAS bf16x8*)(lds + PG8_SA(b, h) + aoff + m * 2048 + k * 1024); } while (0)
; #define PG8_LDB(dst, b, h) do { _Pragma("unroll") for (int n = 0; n < 2; ++n) _Pragma("unroll") for (int k = 0; k < 2; ++k) dst[n][k] = *(const PG8_LAS bf16x8*)(lds + PG8_SB(b, h) + boff + n * 2048 + k * 1024); } while (0)
; #define PG8_MMA(ai, bj, At, Bt) do { __builtin_amdgcn_s_setprio(1); _Pragma("unroll") for (int m = 0; m < 4; ++m) _Pragma("unroll") for (int n = 0; n < 2; ++n) _Pragma("unroll") for (int k = 0; k < 2; ++k) \
;         acc[ai][bj][m][n] = __builtin_amdgcn_mfma_f32_16x16x32_bf16(Bt[n][k], At[m][k], acc[ai][bj][m][n], 0, 0, 0); __builtin_amdgcn_s_setprio(0); } while (0)
; #define PG8_WAIT_V(n) asm volatile("s_waitcnt vmcnt(" #n ")" ::: "memory")
; #define PG8_WAIT_L(n) asm volatile("s_waitcnt lgkmcnt(" #n ")" ::: "memory")
; #define PG8_BAR __builtin_amdgcn_s_barrier()
; #define PG8_SCHED __builtin_amdgcn_sched_barrier(0)
; template <class Epi, class Sched, bool ALIGN_EPI = false, bool SP2 = false>
; __device__ __forceinline__ void gemm_phase(PG8_LAS unsigned char* lds, const Gemm g, const Sched& S, const Epi& E) {
;     ...
;             PG8_WAIT_V(8); PG8_WAIT_L(0); PG8_BAR; PG8_MMA(1, 0, At, B0); PG8_MMA(1, 1, At, B1); PG8_BAR; PG8_SCHED;
;             PG8_LDB(B0, 1, 0); PG8_LDB(B1, 1, 1); PG8_SCHED; PG8_LDA(At, 1, 0); PG8_STAGE(PG8_SA(0, 1), a2 + hstepA, voffA);
;             PG8_WAIT_V(8); PG8_WAIT_L(0); PG8_BAR; PG8_MMA(0, 0, At, B0); PG8_MMA(0, 1, At, B1); PG8_BAR; PG8_SCHED;
	s_setprio 1
	s_waitcnt lgkmcnt(0)
	v_mfma_f32_16x16x32_bf16 v[60:63], v[144:147], v[190:193], v[60:63]
	v_mfma_f32_16x16x32_bf16 v[56:59], v[158:161], v[190:193], v[56:59]
	v_mfma_f32_16x16x32_bf16 v[44:47], v[144:147], v[200:203], v[44:47]
	v_mfma_f32_16x16x32_bf16 v[40:43], v[158:161], v[200:203], v[40:43]
	v_mfma_f32_16x16x32_bf16 v[28:31], v[144:147], v[208:211], v[28:31]
	v_mfma_f32_16x16x32_bf16 v[24:27], v[158:161], v[208:211], v[24:27]
	v_mfma_f32_16x16x32_bf16 v[12:15], v[144:147], v[216:219], v[12:15]
	v_mfma_f32_16x16x32_bf16 v[8:11], v[158:161], v[216:219], v[8:11]
	v_mfma_f32_16x16x32_bf16 v[60:63], v[154:157], v[196:199], v[60:63]
	v_mfma_f32_16x16x32_bf16 v[56:59], v[170:173], v[196:199], v[56:59]
	v_mfma_f32_16x16x32_bf16 v[44:47], v[154:157], v[204:207], v[44:47]
	v_mfma_f32_16x16x32_bf16 v[40:43], v[170:173], v[204:207], v[40:43]
	v_mfma_f32_16x16x32_bf16 v[28:31], v[154:157], v[212:215], v[28:31]
	v_mfma_f32_16x16x32_bf16 v[24:27], v[170:173], v[212:215], v[24:27]
	v_mfma_f32_16x16x32_bf16 v[12:15], v[154:157], v[220:223], v[12:15]
	v_mfma_f32_16x16x32_bf16 v[8:11], v[170:173], v[220:223], v[8:11]
	v_mfma_f32_16x16x32_bf16 v[52:55], v[174:177], v[190:193], v[52:55]
	v_mfma_f32_16x16x32_bf16 v[48:51], v[182:185], v[190:193], v[48:51]
	v_mfma_f32_16x16x32_bf16 v[36:39], v[174:177], v[200:203], v[36:39]
	v_mfma_f32_16x16x32_bf16 v[32:35], v[182:185], v[200:203], v[32:35]
	v_mfma_f32_16x16x32_bf16 v[20:23], v[174:177], v[208:211], v[20:23]
	v_mfma_f32_16x16x32_bf16 v[16:19], v[182:185], v[208:211], v[16:19]
	v_mfma_f32_16x16x32_bf16 v[4:7], v[174:177], v[216:219], v[4:7]
	v_mfma_f32_16x16x32_bf16 v[0:3], v[182:185], v[216:219], v[0:3]
	v_mfma_f32_16x16x32_bf16 v[52:55], v[178:181], v[196:199], v[52:55]
	v_mfma_f32_16x16x32_bf16 v[48:51], v[186:189], v[196:199], v[48:51]
	v_mfma_f32_16x16x32_bf16 v[36:39], v[178:181], v[204:207], v[36:39]
	v_mfma_f32_16x16x32_bf16 v[32:35], v[186:189], v[204:207], v[32:35]
	v_mfma_f32_16x16x32_bf16 v[20:23], v[178:181], v[212:215], v[20:23]
	v_mfma_f32_16x16x32_bf16 v[16:19], v[186:189], v[212:215], v[16:19]
	v_mfma_f32_16x16x32_bf16 v[4:7], v[178:181], v[220:223], v[4:7]
	v_mfma_f32_16x16x32_bf16 v[0:3], v[186:189], v[220:223], v[0:3]
	s_setprio 0
	s_barrier
	s_add_i32 s53, 0, 0x18000
	v_add_u32_e32 v169, s53, v149
	s_add_i32 s54, 0, 0x1c000
	ds_read_b128 v[144:147], v169
	ds_read_b128 v[154:157], v169 offset:1024
	ds_read_b128 v[158:161], v169 offset:2048
	ds_read_b128 v[170:173], v169 offset:3072
	v_add_u32_e32 v169, s54, v149
	ds_read_b128 v[174:177], v169
	ds_read_b128 v[178:181], v169 offset:1024
	ds_read_b128 v[182:185], v169 offset:2048
	ds_read_b128 v[186:189], v169 offset:3072
	s_add_u32 s38, s38, 0x40000
	s_addc_u32 s39, s39, 0
	s_mov_b32 m0, s41
	v_lshl_add_u64 v[232:233], s[38:39], 0, v[134:135]
	ds_read_b128 v[190:193], v153 offset:32768
	ds_read_b128 v[196:199], v153 offset:33792
	ds_read_b128 v[200:203], v153 offset:34816
	ds_read_b128 v[204:207], v153 offset:35840
	ds_read_b128 v[208:211], v153 offset:36864
	ds_read_b128 v[212:215], v153 offset:37888
	ds_read_b128 v[216:219], v153 offset:38912
	ds_read_b128 v[220:223], v153 offset:39936
	global_load_lds_dwordx4 v[232:233], off
	v_lshl_add_u64 v[232:233], s[38:39], 0, v[130:131]
	s_mov_b32 m0, s42
	s_nop 0
	global_load_lds_dwordx4 v[232:233], off
	s_waitcnt vmcnt(8)
	s_waitcnt lgkmcnt(0)
	s_barrier
	s_setprio 1
	s_waitcnt lgkmcnt(0)
	v_mfma_f32_16x16x32_bf16 v[124:127], v[144:147], v[190:193], v[124:127]
	v_mfma_f32_16x16x32_bf16 v[120:123], v[158:161], v[190:193], v[120:123]
	v_mfma_f32_16x16x32_bf16 v[108:111], v[144:147], v[200:203], v[108:111]
	v_mfma_f32_16x16x32_bf16 v[104:107], v[158:161], v[200:203], v[104:107]
	v_mfma_f32_16x16x32_bf16 v[92:95], v[144:147], v[208:211], v[92:95]
	v_mfma_f32_16x16x32_bf16 v[88:91], v[158:161], v[208:211], v[88:91]
	v_mfma_f32_16x16x32_bf16 v[76:79], v[144:147], v[216:219], v[76:79]
	v_mfma_f32_16x16x32_bf16 v[72:75], v[158:161], v[216:219], v[72:75]
	v_mfma_f32_16x16x32_bf16 v[124:127], v[154:157], v[196:199], v[124:127]
	v_mfma_f32_16x16x32_bf16 v[120:123], v[170:173], v[196:199], v[120:123]
	v_mfma_f32_16x16x32_bf16 v[108:111], v[154:157], v[204:207], v[108:111]
	v_mfma_f32_16x16x32_bf16 v[104:107], v[170:173], v[204:207], v[104:107]
	v_mfma_f32_16x16x32_bf16 v[92:95], v[154:157], v[212:215], v[92:95]
	v_mfma_f32_16x16x32_bf16 v[88:91], v[170:173], v[212:215], v[88:91]
	v_mfma_f32_16x16x32_bf16 v[76:79], v[154:157], v[220:223], v[76:79]
	v_mfma_f32_16x16x32_bf16 v[72:75], v[170:173], v[220:223], v[72:75]
	v_mfma_f32_16x16x32_bf16 v[116:119], v[174:177], v[190:193], v[116:119]
	v_mfma_f32_16x16x32_bf16 v[112:115], v[182:185], v[190:193], v[112:115]
	v_mfma_f32_16x16x32_bf16 v[100:103], v[174:177], v[200:203], v[100:103]
	v_mfma_f32_16x16x32_bf16 v[96:99], v[182:185], v[200:203], v[96:99]
	v_mfma_f32_16x16x32_bf16 v[84:87], v[174:177], v[208:211], v[84:87]
	v_mfma_f32_16x16x32_bf16 v[80:83], v[182:185], v[208:211], v[80:83]
	v_mfma_f32_16x16x32_bf16 v[68:71], v[174:177], v[216:219], v[68:71]
	v_mfma_f32_16x16x32_bf16 v[64:67], v[182:185], v[216:219], v[64:67]
	v_mfma_f32_16x16x32_bf16 v[116:119], v[178:181], v[196:199], v[116:119]
	v_mfma_f32_16x16x32_bf16 v[112:115], v[186:189], v[196:199], v[112:115]
	v_mfma_f32_16x16x32_bf16 v[100:103], v[178:181], v[204:207], v[100:103]
	v_mfma_f32_16x16x32_bf16 v[96:99], v[186:189], v[204:207], v[96:99]
	v_mfma_f32_16x16x32_bf16 v[84:87], v[178:181], v[212:215], v[84:87]
	v_mfma_f32_16x16x32_bf16 v[80:83], v[186:189], v[212:215], v[80:83]
	v_mfma_f32_16x16x32_bf16 v[68:71], v[178:181], v[220:223], v[68:71]
	v_mfma_f32_16x16x32_bf16 v[64:67], v[186:189], v[220:223], v[64:67]
	s_setprio 0
	s_barrier
; #define PG8_STAGE(bufoff, gbase, voff) do { _Pragma("unroll") for (int _i = 0; _i < 2; ++_i) \
;         __builtin_amdgcn_global_load_lds((const unsigned*)((const char*)(gbase) + (voff)[_i]), (PG8_LAS unsigned*)(lds + (bufoff) + ldsw + _i * 8192), 16, 0, 0); } while (0)
; #define PG8_LDA(dst, b, h) do { _Pragma("unroll") for (int m = 0; m < 4; ++m) _Pragma("unroll") for (int k = 0; k < 2; ++k) dst[m][k] = *(const PG8_LAS bf16x8*)(lds + PG8_SA(b, h) + aoff + m * 2048 + k * 1024); } while (0)
; #define PG8_WAIT_V(n) asm volatile("s_waitcnt vmcnt(" #n ")" ::: "memory")
; #define PG8_WAIT_L(n) asm volatile("s_waitcnt lgkmcnt(" #n ")" ::: "memory")
; template <class Epi, class Sched, bool ALIGN_EPI = false, bool SP2 = false>
; __device__ __forceinline__ void gemm_phase(PG8_LAS unsigned char* lds, const Gemm g, const Sched& S, const Epi& E) {
;     ...
;         for (int t = 0; t < nt; t += 2) {
;             const bool last = (t == nt - 2);
;             const char* a1 = cA + (size_t)(t + 1) * kstep;
;             const char* a2 = last ? nA : cA + (size_t)(t + 2) * kstep; const char* b2 = last ? nB : cB + (size_t)(t + 2) * kstep;
;             const char* a3 = a2 + kstep; const char* b3 = b2 + kstep;
;             if (last && has_next) S.a_ready(nxt);
;             if constexpr (SP2) {
;             PG8_LDB(B0, 0, 0); PG8_LDB(B1, 0, 1); PG8_SCHED; PG8_LDA(At, 0, 0); PG8_STAGE(PG8_SA(1, 1), a1 + hstepA, voffA);
;             PG8_WAIT_V(8); PG8_WAIT_L(0); PG8_BAR; PG8_MMA(0, 0, At, B0); PG8_MMA(0, 1, At, B1); PG8_BAR; PG8_SCHED;
;             PG8_LDA(At, 0, 1); PG8_STAGE(PG8_SB(0, 0), b2, voffB); PG8_STAGE(PG8_SB(0, 1), b2 + hstepB, voffB); PG8_STAGE(PG8_SA(0, 0), a2, voffA);
;             PG8_WAIT_V(8); PG8_WAIT_L(0); PG8_BAR; PG8_MMA(1, 0, At, B0); PG8_MMA(1, 1, At, B1); PG8_BAR; PG8_SCHED;
;             PG8_LDB(B0, 1, 0); PG8_LDB(B1, 1, 1); PG8_SCHED; PG8_LDA(At, 1, 0); PG8_STAGE(PG8_SA(0, 1), a2 + hstepA, voffA);
;             PG8_WAIT_V(8); PG8_WAIT_L(0); PG8_BAR; PG8_MMA(0, 0, At, B0); PG8_MMA(0, 1, At, B1); PG8_BAR; PG8_SCHED;
;             PG8_LDA(At, 1, 1); PG8_STAGE(PG8_SB(1, 0), b3, voffB); PG8_STAGE(PG8_SB(1, 1), b3 + hstepB, voffB); PG8_STAGE(PG8_SA(1, 0), a3, voffA);
;             PG8_WAIT_V(8); PG8_WAIT_L(0); PG8_BAR; PG8_MMA(1, 0, At, B0); PG8_MMA(1, 1, At, B1); PG8_BAR; PG8_SCHED;
;     ...
;         if constexpr (ALIGN_EPI) { if (wr == 0) PG8_BAR; }
	s_add_i32 s38, s53, s33
	v_lshl_add_u64 v[224:225], v[224:225], 0, s[18:19]
	s_mov_b32 m0, s38
	ds_read_b128 v[190:193], v153 offset:49152
	ds_read_b128 v[196:199], v153 offset:50176
	ds_read_b128 v[200:203], v153 offset:51200
	ds_read_b128 v[204:207], v153 offset:52224
	ds_read_b128 v[208:211], v153 offset:53248
	ds_read_b128 v[212:215], v153 offset:54272
	ds_read_b128 v[216:219], v153 offset:55296
	ds_read_b128 v[220:223], v153 offset:56320
	global_load_lds_dwordx4 v[224:225], off
	s_add_i32 m0, s38, 0x2000
	s_add_u32 s36, s36, 0x40080
	v_lshl_add_u64 v[224:225], v[226:227], 0, s[18:19]
	s_addc_u32 s37, s37, 0
	s_add_i32 s38, s54, s33
	global_load_lds_dwordx4 v[224:225], off
	v_lshl_add_u64 v[224:225], s[36:37], 0, v[132:133]
	s_mov_b32 m0, s38
	s_nop 0
	global_load_lds_dwordx4 v[224:225], off
	v_lshl_add_u64 v[224:225], s[36:37], 0, v[128:129]
	s_add_i32 m0, s38, 0x2000
	s_nop 0
	global_load_lds_dwordx4 v[224:225], off
	v_lshl_add_u64 v[224:225], v[228:229], 0, s[18:19]
	s_mov_b32 m0, s43
	s_nop 0
	global_load_lds_dwordx4 v[224:225], off
	v_lshl_add_u64 v[224:225], v[230:231], 0, s[18:19]
	s_mov_b32 m0, s44
	s_nop 0
	global_load_lds_dwordx4 v[224:225], off
	s_waitcnt vmcnt(8)
	s_waitcnt lgkmcnt(0)
	s_barrier
	s_setprio 1
	s_waitcnt lgkmcnt(0)
	v_mfma_f32_16x16x32_bf16 v[60:63], v[144:147], v[190:193], v[60:63]
	v_mfma_f32_16x16x32_bf16 v[56:59], v[158:161], v[190:193], v[56:59]
	v_mfma_f32_16x16x32_bf16 v[44:47], v[144:147], v[200:203], v[44:47]
	v_mfma_f32_16x16x32_bf16 v[40:43], v[158:161], v[200:203], v[40:43]
	v_mfma_f32_16x16x32_bf16 v[28:31], v[144:147], v[208:211], v[28:31]
	v_mfma_f32_16x16x32_bf16 v[24:27], v[158:161], v[208:211], v[24:27]
	v_mfma_f32_16x16x32_bf16 v[12:15], v[144:147], v[216:219], v[12:15]
	v_mfma_f32_16x16x32_bf16 v[8:11], v[158:161], v[216:219], v[8:11]
	v_mfma_f32_16x16x32_bf16 v[60:63], v[154:157], v[196:199], v[60:63]
	v_mfma_f32_16x16x32_bf16 v[56:59], v[170:173], v[196:199], v[56:59]
	v_mfma_f32_16x16x32_bf16 v[44:47], v[154:157], v[204:207], v[44:47]
	v_mfma_f32_16x16x32_bf16 v[40:43], v[170:173], v[204:207], v[40:43]
	v_mfma_f32_16x16x32_bf16 v[28:31], v[154:157], v[212:215], v[28:31]
	v_mfma_f32_16x16x32_bf16 v[24:27], v[170:173], v[212:215], v[24:27]
	v_mfma_f32_16x16x32_bf16 v[12:15], v[154:157], v[220:223], v[12:15]
	v_mfma_f32_16x16x32_bf16 v[8:11], v[170:173], v[220:223], v[8:11]
	v_mfma_f32_16x16x32_bf16 v[52:55], v[174:177], v[190:193], v[52:55]
	v_mfma_f32_16x16x32_bf16 v[48:51], v[182:185], v[190:193], v[48:51]
	v_mfma_f32_16x16x32_bf16 v[36:39], v[174:177], v[200:203], v[36:39]
	v_mfma_f32_16x16x32_bf16 v[32:35], v[182:185], v[200:203], v[32:35]
	v_mfma_f32_16x16x32_bf16 v[20:23], v[174:177], v[208:211], v[20:23]
	v_mfma_f32_16x16x32_bf16 v[16:19], v[182:185], v[208:211], v[16:19]
	v_mfma_f32_16x16x32_bf16 v[4:7], v[174:177], v[216:219], v[4:7]
	v_mfma_f32_16x16x32_bf16 v[0:3], v[182:185], v[216:219], v[0:3]
	v_mfma_f32_16x16x32_bf16 v[52:55], v[178:181], v[196:199], v[52:55]
	v_mfma_f32_16x16x32_bf16 v[48:51], v[186:189], v[196:199], v[48:51]
	v_mfma_f32_16x16x32_bf16 v[36:39], v[178:181], v[204:207], v[36:39]
	v_mfma_f32_16x16x32_bf16 v[32:35], v[186:189], v[204:207], v[32:35]
	v_mfma_f32_16x16x32_bf16 v[20:23], v[178:181], v[212:215], v[20:23]
	v_mfma_f32_16x16x32_bf16 v[16:19], v[186:189], v[212:215], v[16:19]
	v_mfma_f32_16x16x32_bf16 v[4:7], v[178:181], v[220:223], v[4:7]
	v_mfma_f32_16x16x32_bf16 v[0:3], v[186:189], v[220:223], v[0:3]
	s_setprio 0
	s_barrier
	s_add_i32 s52, s52, 2
	s_add_u32 s34, s34, 0x100
	s_addc_u32 s35, s35, 0
	s_add_u32 s50, s50, 0x100
	s_addc_u32 s51, s51, 0
	s_cmp_gt_u32 s52, 13
	s_cbranch_scc0 .LBB0_521
	s_and_b64 vcc, exec, s[20:21]
	s_cbranch_vccz .LBB0_524
	s_barrier

; #define PG8_STAGE(bufoff, gbase, voff) do { _Pragma("unroll") for (int _i = 0; _i < 2; ++_i) \
;         __builtin_amdgcn_global_load_lds((const unsigned*)((const char*)(gbase) + (voff)[_i]), (PG8_LAS unsigned*)(lds + (bufoff) + ldsw + _i * 8192), 16, 0, 0); } while (0)
; #define PG8_LDA(dst, b, h) do { _Pragma("unroll") for (int m = 0; m < 4; ++m) _Pragma("unroll") for (int k = 0; k < 2; ++k) dst[m][k] = *(const PG8_LAS bf16x8*)(lds + PG8_SA(b, h) + aoff + m * 2048 + k * 1024); } while (0)
; #define PG8_LDB(dst, b, h) do { _Pragma("unroll") for (int n = 0; n < 2; ++n) _Pragma("unroll") for (int k = 0; k < 2; ++k) dst[n][k] = *(const PG8_LAS bf16x8*)(lds + PG8_SB(b, h) + boff + n * 2048 + k * 1024); } while (0)
; #define PG8_MMA(ai, bj, At, Bt) do { __builtin_amdgcn_s_setprio(1); _Pragma("unroll") for (int m = 0; m < 4; ++m) _Pragma("unroll") for (int n = 0; n < 2; ++n) _Pragma("unroll") for (int k = 0; k < 2; ++k) \
;         acc[ai][bj][m][n] = __builtin_amdgcn_mfma_f32_16x16x32_bf16(Bt[n][k], At[m][k], acc[ai][bj][m][n], 0, 0, 0); __builtin_amdgcn_s_setprio(0); } while (0)
; #define PG8_WAIT_V(n) asm volatile("s_waitcnt vmcnt(" #n ")" ::: "memory")
; #define PG8_WAIT_L(n) asm volatile("s_waitcnt lgkmcnt(" #n ")" ::: "memory")
; #define PG8_BAR __builtin_amdgcn_s_barrier()
; #define PG8_SCHED __builtin_amdgcn_sched_barrier(0)
; template <class Epi, class Sched, bool ALIGN_EPI = false, bool SP2 = false>
; __device__ __forceinline__ void gemm_phase(PG8_LAS unsigned char* lds, const Gemm g, const Sched& S, const Epi& E) {
;     ...
;             const bool last = (t == nt - 2);
;             const char* a1 = cA + (size_t)(t + 1) * kstep;
;             const char* a2 = last ? nA : cA + (size_t)(t + 2) * kstep; const char* b2 = last ? nB : cB + (size_t)(t + 2) * kstep;
;             const char* a3 = a2 + kstep; const char* b3 = b2 + kstep;
;             if (last && has_next) S.a_ready(nxt);
;             if constexpr (SP2) {
;             PG8_LDB(B0, 0, 0); PG8_LDB(B1, 0, 1); PG8_SCHED; PG8_LDA(At, 0, 0); PG8_STAGE(PG8_SA(1, 1), a1 + hstepA, voffA);
;             PG8_WAIT_V(8); PG8_WAIT_L(0); PG8_BAR; PG8_MMA(0, 0, At, B0); PG8_MMA(0, 1, At, B1); PG8_BAR; PG8_SCHED;
;             PG8_LDA(At, 0, 1); PG8_STAGE(PG8_SB(0, 0), b2, voffB); PG8_STAGE(PG8_SB(0, 1), b2 + hstepB, voffB); PG8_STAGE(PG8_SA(0, 0), a2, voffA);
.LBB0_541:
	ds_read_b128 v[144:147], v153
	ds_read_b128 v[156:159], v153 offset:1024
	ds_read_b128 v[170:173], v153 offset:2048
	ds_read_b128 v[174:177], v153 offset:3072
	ds_read_b128 v[178:181], v154
	ds_read_b128 v[182:185], v154 offset:1024
	ds_read_b128 v[186:189], v154 offset:2048
	ds_read_b128 v[190:193], v154 offset:3072
	s_add_u32 s40, s38, 0xfffc0080
	s_addc_u32 s41, s39, -1
	s_cmp_eq_u32 s60, 12
	s_cselect_b32 s43, s29, s41
	s_cselect_b32 s42, s52, s40
	s_cselect_b32 s41, s27, s55
	s_cselect_b32 s40, s53, s54
	v_lshl_add_u64 v[148:149], s[38:39], 0, v[136:137]
	s_add_i32 m0, s3, 0xc000
	ds_read_b128 v[196:199], v155
	ds_read_b128 v[200:203], v155 offset:1024
	ds_read_b128 v[204:207], v155 offset:2048
	ds_read_b128 v[208:211], v155 offset:3072
	ds_read_b128 v[212:215], v155 offset:4096
	ds_read_b128 v[216:219], v155 offset:5120
	ds_read_b128 v[220:223], v155 offset:6144
	ds_read_b128 v[224:227], v155 offset:7168
	global_load_lds_dwordx4 v[148:149], off
	v_lshl_add_u64 v[148:149], s[38:39], 0, v[138:139]
	s_add_i32 m0, s3, 0xe000
	s_nop 0
	global_load_lds_dwordx4 v[148:149], off
	s_waitcnt vmcnt(8)
	s_waitcnt lgkmcnt(0)
	s_barrier
	s_setprio 1
	s_waitcnt lgkmcnt(0)
	v_mfma_f32_16x16x32_bf16 v[124:127], v[144:147], v[196:199], v[124:127]
	v_mfma_f32_16x16x32_bf16 v[120:123], v[170:173], v[196:199], v[120:123]
	v_mfma_f32_16x16x32_bf16 v[108:111], v[144:147], v[204:207], v[108:111]
	v_mfma_f32_16x16x32_bf16 v[104:107], v[170:173], v[204:207], v[104:107]
	v_mfma_f32_16x16x32_bf16 v[92:95], v[144:147], v[212:215], v[92:95]
	v_mfma_f32_16x16x32_bf16 v[88:91], v[170:173], v[212:215], v[88:91]
	v_mfma_f32_16x16x32_bf16 v[76:79], v[144:147], v[220:223], v[76:79]
	v_mfma_f32_16x16x32_bf16 v[72:75], v[170:173], v[220:223], v[72:75]
	v_mfma_f32_16x16x32_bf16 v[124:127], v[156:159], v[200:203], v[124:127]
	v_mfma_f32_16x16x32_bf16 v[120:123], v[174:177], v[200:203], v[120:123]
	v_mfma_f32_16x16x32_bf16 v[108:111], v[156:159], v[208:211], v[108:111]
	v_mfma_f32_16x16x32_bf16 v[104:107], v[174:177], v[208:211], v[104:107]
	v_mfma_f32_16x16x32_bf16 v[92:95], v[156:159], v[216:219], v[92:95]
	v_mfma_f32_16x16x32_bf16 v[88:91], v[174:177], v[216:219], v[88:91]
	v_mfma_f32_16x16x32_bf16 v[76:79], v[156:159], v[224:227], v[76:79]
	v_mfma_f32_16x16x32_bf16 v[72:75], v[174:177], v[224:227], v[72:75]
	v_mfma_f32_16x16x32_bf16 v[116:119], v[178:181], v[196:199], v[116:119]
	v_mfma_f32_16x16x32_bf16 v[112:115], v[186:189], v[196:199], v[112:115]
	v_mfma_f32_16x16x32_bf16 v[100:103], v[178:181], v[204:207], v[100:103]
	v_mfma_f32_16x16x32_bf16 v[96:99], v[186:189], v[204:207], v[96:99]
	v_mfma_f32_16x16x32_bf16 v[84:87], v[178:181], v[212:215], v[84:87]
	v_mfma_f32_16x16x32_bf16 v[80:83], v[186:189], v[212:215], v[80:83]
	v_mfma_f32_16x16x32_bf16 v[68:71], v[178:181], v[220:223], v[68:71]
	v_mfma_f32_16x16x32_bf16 v[64:67], v[186:189], v[220:223], v[64:67]
	v_mfma_f32_16x16x32_bf16 v[116:119], v[182:185], v[200:203], v[116:119]
	v_mfma_f32_16x16x32_bf16 v[112:115], v[190:193], v[200:203], v[112:115]
	v_mfma_f32_16x16x32_bf16 v[100:103], v[182:185], v[208:211], v[100:103]
	v_mfma_f32_16x16x32_bf16 v[96:99], v[190:193], v[208:211], v[96:99]
	v_mfma_f32_16x16x32_bf16 v[84:87], v[182:185], v[216:219], v[84:87]
	v_mfma_f32_16x16x32_bf16 v[80:83], v[190:193], v[216:219], v[80:83]
	v_mfma_f32_16x16x32_bf16 v[68:71], v[182:185], v[224:227], v[68:71]
	v_mfma_f32_16x16x32_bf16 v[64:67], v[190:193], v[224:227], v[64:67]
	s_setprio 0
	s_barrier
	s_add_i32 s61, s56, s0
	v_lshl_add_u64 v[148:149], s[40:41], 0, v[132:133]
	s_mov_b32 m0, s61
	ds_read_b128 v[196:199], v155 offset:16384
	ds_read_b128 v[200:203], v155 offset:17408
	ds_read_b128 v[204:207], v155 offset:18432
	ds_read_b128 v[208:211], v155 offset:19456
	ds_read_b128 v[212:215], v155 offset:20480
	ds_read_b128 v[216:219], v155 offset:21504
	ds_read_b128 v[220:223], v155 offset:22528
	ds_read_b128 v[224:227], v155 offset:23552
	global_load_lds_dwordx4 v[148:149], off
	s_add_i32 m0, s61, 0x2000
	s_add_u32 s62, s40, 0x40000
	v_lshl_add_u64 v[160:161], s[40:41], 0, v[128:129]
	s_addc_u32 s63, s41, 0
	s_add_i32 s61, s50, s0
	global_load_lds_dwordx4 v[160:161], off
	v_lshl_add_u64 v[228:229], s[62:63], 0, v[132:133]
	s_mov_b32 m0, s61
	v_lshl_add_u64 v[230:231], s[42:43], 0, v[130:131]
	global_load_lds_dwordx4 v[228:229], off
	v_lshl_add_u64 v[228:229], s[62:63], 0, v[128:129]
	s_add_i32 m0, s61, 0x2000
	s_nop 0
	global_load_lds_dwordx4 v[228:229], off
	v_lshl_add_u64 v[228:229], s[42:43], 0, v[134:135]
	s_mov_b32 m0, s3
	s_nop 0
	global_load_lds_dwordx4 v[228:229], off
	s_mov_b32 m0, s33
	s_nop 0
	global_load_lds_dwordx4 v[230:231], off
	s_waitcnt vmcnt(8)
	s_waitcnt lgkmcnt(0)
	s_barrier
; #define PG8_STAGE(bufoff, gbase, voff) do { _Pragma("unroll") for (int _i = 0; _i < 2; ++_i) \
;         __builtin_amdgcn_global_load_lds((const unsigned*)((const char*)(gbase) + (voff)[_i]), (PG8_LAS unsigned*)(lds + (bufoff) + ldsw + _i * 8192), 16, 0, 0); } while (0)
; #define PG8_LDA(dst, b, h) do { _Pragma("unroll") for (int m = 0; m < 4; ++m) _Pragma("unroll") for (int k = 0; k < 2; ++k) dst[m][k] = *(const PG8_LAS bf16x8*)(lds + PG8_SA(b, h) + aoff + m * 2048 + k * 1024); } while (0)
; #define PG8_LDB(dst, b, h) do { _Pragma("unroll") for (int n = 0; n < 2; ++n) _Pragma("unroll") for (int k = 0; k < 2; ++k) dst[n][k] = *(const PG8_LAS bf16x8*)(lds + PG8_SB(b, h) + boff + n * 2048 + k * 1024); } while (0)
; #define PG8_MMA(ai, bj, At, Bt) do { __builtin_amdgcn_s_setprio(1); _Pragma("unroll") for (int m = 0; m < 4; ++m) _Pragma("unroll") for (int n = 0; n < 2; ++n) _Pragma("unroll") for (int k = 0; k < 2; ++k) \
;         acc[ai][bj][m][n] = __builtin_amdgcn_mfma_f32_16x16x32_bf16(Bt[n][k], At[m][k], acc[ai][bj][m][n], 0, 0, 0); __builtin_amdgcn_s_setprio(0); } while (0)
; #define PG8_WAIT_V(n) asm volatile("s_waitcnt vmcnt(" #n ")" ::: "memory")
; #define PG8_WAIT_L(n) asm volatile("s_waitcnt lgkmcnt(" #n ")" ::: "memory")
; #define PG8_BAR __builtin_amdgcn_s_barrier()
; #define PG8_SCHED __builtin_amdgcn_sched_barrier(0)
; template <class Epi, class Sched, bool ALIGN_EPI = false, bool SP2 = false>
; __device__ __forceinline__ void gemm_phase(PG8_LAS unsigned char* lds, const Gemm g, const Sched& S, const Epi& E) {
;     ...
;             PG8_WAIT_V(8); PG8_WAIT_L(0); PG8_BAR; PG8_MMA(1, 0, At, B0); PG8_MMA(1, 1, At, B1); PG8_BAR; PG8_SCHED;
;             PG8_LDB(B0, 1, 0); PG8_LDB(B1, 1, 1); PG8_SCHED; PG8_LDA(At, 1, 0); PG8_STAGE(PG8_SA(0, 1), a2 + hstepA, voffA);
;             PG8_WAIT_V(8); PG8_WAIT_L(0); PG8_BAR; PG8_MMA(0, 0, At, B0); PG8_MMA(0, 1, At, B1); PG8_BAR; PG8_SCHED;
	s_setprio 1
	s_waitcnt lgkmcnt(0)
	v_mfma_f32_16x16x32_bf16 v[60:63], v[144:147], v[196:199], v[60:63]
	v_mfma_f32_16x16x32_bf16 v[56:59], v[170:173], v[196:199], v[56:59]
	v_mfma_f32_16x16x32_bf16 v[44:47], v[144:147], v[204:207], v[44:47]
	v_mfma_f32_16x16x32_bf16 v[40:43], v[170:173], v[204:207], v[40:43]
	v_mfma_f32_16x16x32_bf16 v[28:31], v[144:147], v[212:215], v[28:31]
	v_mfma_f32_16x16x32_bf16 v[24:27], v[170:173], v[212:215], v[24:27]
	v_mfma_f32_16x16x32_bf16 v[12:15], v[144:147], v[220:223], v[12:15]
	v_mfma_f32_16x16x32_bf16 v[8:11], v[170:173], v[220:223], v[8:11]
	v_mfma_f32_16x16x32_bf16 v[60:63], v[156:159], v[200:203], v[60:63]
	v_mfma_f32_16x16x32_bf16 v[56:59], v[174:177], v[200:203], v[56:59]
	v_mfma_f32_16x16x32_bf16 v[44:47], v[156:159], v[208:211], v[44:47]
	v_mfma_f32_16x16x32_bf16 v[40:43], v[174:177], v[208:211], v[40:43]
	v_mfma_f32_16x16x32_bf16 v[28:31], v[156:159], v[216:219], v[28:31]
	v_mfma_f32_16x16x32_bf16 v[24:27], v[174:177], v[216:219], v[24:27]
	v_mfma_f32_16x16x32_bf16 v[12:15], v[156:159], v[224:227], v[12:15]
	v_mfma_f32_16x16x32_bf16 v[8:11], v[174:177], v[224:227], v[8:11]
	v_mfma_f32_16x16x32_bf16 v[52:55], v[178:181], v[196:199], v[52:55]
	v_mfma_f32_16x16x32_bf16 v[48:51], v[186:189], v[196:199], v[48:51]
	v_mfma_f32_16x16x32_bf16 v[36:39], v[178:181], v[204:207], v[36:39]
	v_mfma_f32_16x16x32_bf16 v[32:35], v[186:189], v[204:207], v[32:35]
	v_mfma_f32_16x16x32_bf16 v[20:23], v[178:181], v[212:215], v[20:23]
	v_mfma_f32_16x16x32_bf16 v[16:19], v[186:189], v[212:215], v[16:19]
	v_mfma_f32_16x16x32_bf16 v[4:7], v[178:181], v[220:223], v[4:7]
	v_mfma_f32_16x16x32_bf16 v[0:3], v[186:189], v[220:223], v[0:3]
	v_mfma_f32_16x16x32_bf16 v[52:55], v[182:185], v[200:203], v[52:55]
	v_mfma_f32_16x16x32_bf16 v[48:51], v[190:193], v[200:203], v[48:51]
	v_mfma_f32_16x16x32_bf16 v[36:39], v[182:185], v[208:211], v[36:39]
	v_mfma_f32_16x16x32_bf16 v[32:35], v[190:193], v[208:211], v[32:35]
	v_mfma_f32_16x16x32_bf16 v[20:23], v[182:185], v[216:219], v[20:23]
	v_mfma_f32_16x16x32_bf16 v[16:19], v[190:193], v[216:219], v[16:19]
	v_mfma_f32_16x16x32_bf16 v[4:7], v[182:185], v[224:227], v[4:7]
	v_mfma_f32_16x16x32_bf16 v[0:3], v[190:193], v[224:227], v[0:3]
	s_setprio 0
	s_barrier
	s_add_i32 s61, 0, 0x18000
	v_add_u32_e32 v169, s61, v151
	s_add_i32 s62, 0, 0x1c000
	ds_read_b128 v[144:147], v169
	ds_read_b128 v[156:159], v169 offset:1024
	ds_read_b128 v[170:173], v169 offset:2048
	ds_read_b128 v[174:177], v169 offset:3072
	v_add_u32_e32 v169, s62, v151
	ds_read_b128 v[178:181], v169
	ds_read_b128 v[182:185], v169 offset:1024
	ds_read_b128 v[186:189], v169 offset:2048
	ds_read_b128 v[190:193], v169 offset:3072
	s_add_u32 s42, s42, 0x40000
	s_addc_u32 s43, s43, 0
	s_mov_b32 m0, s37
	v_lshl_add_u64 v[232:233], s[42:43], 0, v[134:135]
	ds_read_b128 v[196:199], v155 offset:32768
	ds_read_b128 v[200:203], v155 offset:33792
	ds_read_b128 v[204:207], v155 offset:34816
	ds_read_b128 v[208:211], v155 offset:35840
	ds_read_b128 v[212:215], v155 offset:36864
	ds_read_b128 v[216:219], v155 offset:37888
	ds_read_b128 v[220:223], v155 offset:38912
	ds_read_b128 v[224:227], v155 offset:39936
	global_load_lds_dwordx4 v[232:233], off
	v_lshl_add_u64 v[232:233], s[42:43], 0, v[130:131]
	s_mov_b32 m0, s47
	s_nop 0
	global_load_lds_dwordx4 v[232:233], off
	s_waitcnt vmcnt(8)
	s_waitcnt lgkmcnt(0)
	s_barrier
	s_setprio 1
	s_waitcnt lgkmcnt(0)
	v_mfma_f32_16x16x32_bf16 v[124:127], v[144:147], v[196:199], v[124:127]
	v_mfma_f32_16x16x32_bf16 v[120:123], v[170:173], v[196:199], v[120:123]
	v_mfma_f32_16x16x32_bf16 v[108:111], v[144:147], v[204:207], v[108:111]
	v_mfma_f32_16x16x32_bf16 v[104:107], v[170:173], v[204:207], v[104:107]
	v_mfma_f32_16x16x32_bf16 v[92:95], v[144:147], v[212:215], v[92:95]
	v_mfma_f32_16x16x32_bf16 v[88:91], v[170:173], v[212:215], v[88:91]
	v_mfma_f32_16x16x32_bf16 v[76:79], v[144:147], v[220:223], v[76:79]
	v_mfma_f32_16x16x32_bf16 v[72:75], v[170:173], v[220:223], v[72:75]
	v_mfma_f32_16x16x32_bf16 v[124:127], v[156:159], v[200:203], v[124:127]
	v_mfma_f32_16x16x32_bf16 v[120:123], v[174:177], v[200:203], v[120:123]
	v_mfma_f32_16x16x32_bf16 v[108:111], v[156:159], v[208:211], v[108:111]
	v_mfma_f32_16x16x32_bf16 v[104:107], v[174:177], v[208:211], v[104:107]
	v_mfma_f32_16x16x32_bf16 v[92:95], v[156:159], v[216:219], v[92:95]
	v_mfma_f32_16x16x32_bf16 v[88:91], v[174:177], v[216:219], v[88:91]
	v_mfma_f32_16x16x32_bf16 v[76:79], v[156:159], v[224:227], v[76:79]
	v_mfma_f32_16x16x32_bf16 v[72:75], v[174:177], v[224:227], v[72:75]
	v_mfma_f32_16x16x32_bf16 v[116:119], v[178:181], v[196:199], v[116:119]
	v_mfma_f32_16x16x32_bf16 v[112:115], v[186:189], v[196:199], v[112:115]
	v_mfma_f32_16x16x32_bf16 v[100:103], v[178:181], v[204:207], v[100:103]
	v_mfma_f32_16x16x32_bf16 v[96:99], v[186:189], v[204:207], v[96:99]
	v_mfma_f32_16x16x32_bf16 v[84:87], v[178:181], v[212:215], v[84:87]
	v_mfma_f32_16x16x32_bf16 v[80:83], v[186:189], v[212:215], v[80:83]
	v_mfma_f32_16x16x32_bf16 v[68:71], v[178:181], v[220:223], v[68:71]
	v_mfma_f32_16x16x32_bf16 v[64:67], v[186:189], v[220:223], v[64:67]
	v_mfma_f32_16x16x32_bf16 v[116:119], v[182:185], v[200:203], v[116:119]
	v_mfma_f32_16x16x32_bf16 v[112:115], v[190:193], v[200:203], v[112:115]
	v_mfma_f32_16x16x32_bf16 v[100:103], v[182:185], v[208:211], v[100:103]
	v_mfma_f32_16x16x32_bf16 v[96:99], v[190:193], v[208:211], v[96:99]
	v_mfma_f32_16x16x32_bf16 v[84:87], v[182:185], v[216:219], v[84:87]
	v_mfma_f32_16x16x32_bf16 v[80:83], v[190:193], v[216:219], v[80:83]
	v_mfma_f32_16x16x32_bf16 v[68:71], v[182:185], v[224:227], v[68:71]
	v_mfma_f32_16x16x32_bf16 v[64:67], v[190:193], v[224:227], v[64:67]
	s_setprio 0
	s_barrier
; #define PG8_STAGE(bufoff, gbase, voff) do { _Pragma("unroll") for (int _i = 0; _i < 2; ++_i) \
;         __builtin_amdgcn_global_load_lds((const unsigned*)((const char*)(gbase) + (voff)[_i]), (PG8_LAS unsigned*)(lds + (bufoff) + ldsw + _i * 8192), 16, 0, 0); } while (0)
; #define PG8_LDA(dst, b, h) do { _Pragma("unroll") for (int m = 0; m < 4; ++m) _Pragma("unroll") for (int k = 0; k < 2; ++k) dst[m][k] = *(const PG8_LAS bf16x8*)(lds + PG8_SA(b, h) + aoff + m * 2048 + k * 1024); } while (0)
; #define PG8_WAIT_V(n) asm volatile("s_waitcnt vmcnt(" #n ")" ::: "memory")
; #define PG8_WAIT_L(n) asm volatile("s_waitcnt lgkmcnt(" #n ")" ::: "memory")
; template <class Epi, class Sched, bool ALIGN_EPI = false, bool SP2 = false>
; __device__ __forceinline__ void gemm_phase(PG8_LAS unsigned char* lds, const Gemm g, const Sched& S, const Epi& E) {
;     ...
;         for (int t = 0; t < nt; t += 2) {
;             const bool last = (t == nt - 2);
;             const char* a1 = cA + (size_t)(t + 1) * kstep;
;             const char* a2 = last ? nA : cA + (size_t)(t + 2) * kstep; const char* b2 = last ? nB : cB + (size_t)(t + 2) * kstep;
;             const char* a3 = a2 + kstep; const char* b3 = b2 + kstep;
;             if (last && has_next) S.a_ready(nxt);
;             if constexpr (SP2) {
;             PG8_LDB(B0, 0, 0); PG8_LDB(B1, 0, 1); PG8_SCHED; PG8_LDA(At, 0, 0); PG8_STAGE(PG8_SA(1, 1), a1 + hstepA, voffA);
;             PG8_WAIT_V(8); PG8_WAIT_L(0); PG8_BAR; PG8_MMA(0, 0, At, B0); PG8_MMA(0, 1, At, B1); PG8_BAR; PG8_SCHED;
;             PG8_LDA(At, 0, 1); PG8_STAGE(PG8_SB(0, 0), b2, voffB); PG8_STAGE(PG8_SB(0, 1), b2 + hstepB, voffB); PG8_STAGE(PG8_SA(0, 0), a2, voffA);
;             PG8_WAIT_V(8); PG8_WAIT_L(0); PG8_BAR; PG8_MMA(1, 0, At, B0); PG8_MMA(1, 1, At, B1); PG8_BAR; PG8_SCHED;
;             PG8_LDB(B0, 1, 0); PG8_LDB(B1, 1, 1); PG8_SCHED; PG8_LDA(At, 1, 0); PG8_STAGE(PG8_SA(0, 1), a2 + hstepA, voffA);
;             PG8_WAIT_V(8); PG8_WAIT_L(0); PG8_BAR; PG8_MMA(0, 0, At, B0); PG8_MMA(0, 1, At, B1); PG8_BAR; PG8_SCHED;
;             PG8_LDA(At, 1, 1); PG8_STAGE(PG8_SB(1, 0), b3, voffB); PG8_STAGE(PG8_SB(1, 1), b3 + hstepB, voffB); PG8_STAGE(PG8_SA(1, 0), a3, voffA);
;             PG8_WAIT_V(8); PG8_WAIT_L(0); PG8_BAR; PG8_MMA(1, 0, At, B0); PG8_MMA(1, 1, At, B1); PG8_BAR; PG8_SCHED;
;     ...
;         if constexpr (ALIGN_EPI) { if (wr == 0) PG8_BAR; }
	s_add_i32 s42, s61, s0
	v_lshl_add_u64 v[148:149], v[148:149], 0, s[20:21]
	s_mov_b32 m0, s42
	ds_read_b128 v[196:199], v155 offset:49152
	ds_read_b128 v[200:203], v155 offset:50176
	ds_read_b128 v[204:207], v155 offset:51200
	ds_read_b128 v[208:211], v155 offset:52224
	ds_read_b128 v[212:215], v155 offset:53248
	ds_read_b128 v[216:219], v155 offset:54272
	ds_read_b128 v[220:223], v155 offset:55296
	ds_read_b128 v[224:227], v155 offset:56320
	global_load_lds_dwordx4 v[148:149], off
	s_add_i32 m0, s42, 0x2000
	s_add_u32 s40, s40, 0x40080
	v_lshl_add_u64 v[148:149], v[160:161], 0, s[20:21]
	s_addc_u32 s41, s41, 0
	s_add_i32 s42, s62, s0
	global_load_lds_dwordx4 v[148:149], off
	v_lshl_add_u64 v[148:149], s[40:41], 0, v[132:133]
	s_mov_b32 m0, s42
	s_nop 0
	global_load_lds_dwordx4 v[148:149], off
	v_lshl_add_u64 v[148:149], s[40:41], 0, v[128:129]
	s_add_i32 m0, s42, 0x2000
	s_nop 0
	global_load_lds_dwordx4 v[148:149], off
	v_lshl_add_u64 v[148:149], v[228:229], 0, s[20:21]
	s_mov_b32 m0, s48
	s_nop 0
	global_load_lds_dwordx4 v[148:149], off
	v_lshl_add_u64 v[148:149], v[230:231], 0, s[20:21]
	s_mov_b32 m0, s49
	s_nop 0
	global_load_lds_dwordx4 v[148:149], off
	s_waitcnt vmcnt(8)
	s_waitcnt lgkmcnt(0)
	s_barrier
	s_setprio 1
	s_waitcnt lgkmcnt(0)
	v_mfma_f32_16x16x32_bf16 v[60:63], v[144:147], v[196:199], v[60:63]
	v_mfma_f32_16x16x32_bf16 v[56:59], v[170:173], v[196:199], v[56:59]
	v_mfma_f32_16x16x32_bf16 v[44:47], v[144:147], v[204:207], v[44:47]
	v_mfma_f32_16x16x32_bf16 v[40:43], v[170:173], v[204:207], v[40:43]
	v_mfma_f32_16x16x32_bf16 v[28:31], v[144:147], v[212:215], v[28:31]
	v_mfma_f32_16x16x32_bf16 v[24:27], v[170:173], v[212:215], v[24:27]
	v_mfma_f32_16x16x32_bf16 v[12:15], v[144:147], v[220:223], v[12:15]
	v_mfma_f32_16x16x32_bf16 v[8:11], v[170:173], v[220:223], v[8:11]
	v_mfma_f32_16x16x32_bf16 v[60:63], v[156:159], v[200:203], v[60:63]
	v_mfma_f32_16x16x32_bf16 v[56:59], v[174:177], v[200:203], v[56:59]
	v_mfma_f32_16x16x32_bf16 v[44:47], v[156:159], v[208:211], v[44:47]
	v_mfma_f32_16x16x32_bf16 v[40:43], v[174:177], v[208:211], v[40:43]
	v_mfma_f32_16x16x32_bf16 v[28:31], v[156:159], v[216:219], v[28:31]
	v_mfma_f32_16x16x32_bf16 v[24:27], v[174:177], v[216:219], v[24:27]
	v_mfma_f32_16x16x32_bf16 v[12:15], v[156:159], v[224:227], v[12:15]
	v_mfma_f32_16x16x32_bf16 v[8:11], v[174:177], v[224:227], v[8:11]
	v_mfma_f32_16x16x32_bf16 v[52:55], v[178:181], v[196:199], v[52:55]
	v_mfma_f32_16x16x32_bf16 v[48:51], v[186:189], v[196:199], v[48:51]
	v_mfma_f32_16x16x32_bf16 v[36:39], v[178:181], v[204:207], v[36:39]
	v_mfma_f32_16x16x32_bf16 v[32:35], v[186:189], v[204:207], v[32:35]
	v_mfma_f32_16x16x32_bf16 v[20:23], v[178:181], v[212:215], v[20:23]
	v_mfma_f32_16x16x32_bf16 v[16:19], v[186:189], v[212:215], v[16:19]
	v_mfma_f32_16x16x32_bf16 v[4:7], v[178:181], v[220:223], v[4:7]
	v_mfma_f32_16x16x32_bf16 v[0:3], v[186:189], v[220:223], v[0:3]
	v_mfma_f32_16x16x32_bf16 v[52:55], v[182:185], v[200:203], v[52:55]
	v_mfma_f32_16x16x32_bf16 v[48:51], v[190:193], v[200:203], v[48:51]
	v_mfma_f32_16x16x32_bf16 v[36:39], v[182:185], v[208:211], v[36:39]
	v_mfma_f32_16x16x32_bf16 v[32:35], v[190:193], v[208:211], v[32:35]
	v_mfma_f32_16x16x32_bf16 v[20:23], v[182:185], v[216:219], v[20:23]
	v_mfma_f32_16x16x32_bf16 v[16:19], v[190:193], v[216:219], v[16:19]
	v_mfma_f32_16x16x32_bf16 v[4:7], v[182:185], v[224:227], v[4:7]
	v_mfma_f32_16x16x32_bf16 v[0:3], v[190:193], v[224:227], v[0:3]
	s_setprio 0
	s_barrier
	s_add_i32 s60, s60, 2
	s_add_u32 s38, s38, 0x100
	s_addc_u32 s39, s39, 0
	s_add_u32 s54, s54, 0x100
	s_addc_u32 s55, s55, 0
	s_cmp_gt_u32 s60, 13
	s_cbranch_scc0 .LBB0_541
	s_and_b64 vcc, exec, s[22:23]
	s_cbranch_vccz .LBB0_544
	s_barrier

; #define PG8_STAGE(bufoff, gbase, voff) do { _Pragma("unroll") for (int _i = 0; _i < 2; ++_i) \
;         __builtin_amdgcn_global_load_lds((const unsigned*)((const char*)(gbase) + (voff)[_i]), (PG8_LAS unsigned*)(lds + (bufoff) + ldsw + _i * 8192), 16, 0, 0); } while (0)
; #define PG8_LDA(dst, b, h) do { _Pragma("unroll") for (int m = 0; m < 4; ++m) _Pragma("unroll") for (int k = 0; k < 2; ++k) dst[m][k] = *(const PG8_LAS bf16x8*)(lds + PG8_SA(b, h) + aoff + m * 2048 + k * 1024); } while (0)
; #define PG8_LDB(dst, b, h) do { _Pragma("unroll") for (int n = 0; n < 2; ++n) _Pragma("unroll") for (int k = 0; k < 2; ++k) dst[n][k] = *(const PG8_LAS bf16x8*)(lds + PG8_SB(b, h) + boff + n * 2048 + k * 1024); } while (0)
; #define PG8_MMA(ai, bj, At, Bt) do { __builtin_amdgcn_s_setprio(1); _Pragma("unroll") for (int m = 0; m < 4; ++m) _Pragma("unroll") for (int n = 0; n < 2; ++n) _Pragma("unroll") for (int k = 0; k < 2; ++k) \
;         acc[ai][bj][m][n] = __builtin_amdgcn_mfma_f32_16x16x32_bf16(Bt[n][k], At[m][k], acc[ai][bj][m][n], 0, 0, 0); __builtin_amdgcn_s_setprio(0); } while (0)
; #define PG8_WAIT_V(n) asm volatile("s_waitcnt vmcnt(" #n ")" ::: "memory")
; #define PG8_WAIT_L(n) asm volatile("s_waitcnt lgkmcnt(" #n ")" ::: "memory")
; #define PG8_BAR __builtin_amdgcn_s_barrier()
; #define PG8_SCHED __builtin_amdgcn_sched_barrier(0)
; template <class Epi, class Sched, bool ALIGN_EPI = false, bool SP2 = false>
; __device__ __forceinline__ void gemm_phase(PG8_LAS unsigned char* lds, const Gemm g, const Sched& S, const Epi& E) {
;     ...
;             const bool last = (t == nt - 2);
;             const char* a1 = cA + (size_t)(t + 1) * kstep;
;             const char* a2 = last ? nA : cA + (size_t)(t + 2) * kstep; const char* b2 = last ? nB : cB + (size_t)(t + 2) * kstep;
;             const char* a3 = a2 + kstep; const char* b3 = b2 + kstep;
;             if (last && has_next) S.a_ready(nxt);
;             if constexpr (SP2) {
;             PG8_LDB(B0, 0, 0); PG8_LDB(B1, 0, 1); PG8_SCHED; PG8_LDA(At, 0, 0); PG8_STAGE(PG8_SA(1, 1), a1 + hstepA, voffA);
;             PG8_WAIT_V(8); PG8_WAIT_L(0); PG8_BAR; PG8_MMA(0, 0, At, B0); PG8_MMA(0, 1, At, B1); PG8_BAR; PG8_SCHED;
;             PG8_LDA(At, 0, 1); PG8_STAGE(PG8_SB(0, 0), b2, voffB); PG8_STAGE(PG8_SB(0, 1), b2 + hstepB, voffB); PG8_STAGE(PG8_SA(0, 0), a2, voffA);
.LBB0_613:
	ds_read_b128 v[128:131], v161
	ds_read_b128 v[132:135], v161 offset:1024
	ds_read_b128 v[136:139], v161 offset:2048
	ds_read_b128 v[140:143], v161 offset:3072
	ds_read_b128 v[172:175], v169
	ds_read_b128 v[176:179], v169 offset:1024
	ds_read_b128 v[180:183], v169 offset:2048
	ds_read_b128 v[184:187], v169 offset:3072
	s_add_u32 s42, s40, 0xfff80080
	s_addc_u32 s43, s41, -1
	s_cmp_eq_u32 s64, 28
	s_cselect_b32 s45, s31, s43
	s_cselect_b32 s44, s60, s42
	s_cselect_b32 s43, s29, s63
	s_cselect_b32 s42, s61, s62
	v_lshl_add_u64 v[156:157], s[40:41], 0, v[148:149]
	s_add_i32 m0, s39, 0xc000
	ds_read_b128 v[188:191], v170
	ds_read_b128 v[196:199], v170 offset:1024
	ds_read_b128 v[200:203], v170 offset:2048
	ds_read_b128 v[204:207], v170 offset:3072
	ds_read_b128 v[208:211], v170 offset:4096
	ds_read_b128 v[212:215], v170 offset:5120
	ds_read_b128 v[216:219], v170 offset:6144
	ds_read_b128 v[220:223], v170 offset:7168
	global_load_lds_dwordx4 v[156:157], off
	v_lshl_add_u64 v[156:157], s[40:41], 0, v[150:151]
	s_add_i32 m0, s39, 0xe000
	s_nop 0
	global_load_lds_dwordx4 v[156:157], off
	s_waitcnt vmcnt(8)
	s_waitcnt lgkmcnt(0)
	s_barrier
	s_setprio 1
	s_waitcnt lgkmcnt(0)
	v_mfma_f32_16x16x32_bf16 v[124:127], v[128:131], v[188:191], v[124:127]
	v_mfma_f32_16x16x32_bf16 v[120:123], v[136:139], v[188:191], v[120:123]
	v_mfma_f32_16x16x32_bf16 v[112:115], v[128:131], v[200:203], v[112:115]
	v_mfma_f32_16x16x32_bf16 v[108:111], v[136:139], v[200:203], v[108:111]
	v_mfma_f32_16x16x32_bf16 v[96:99], v[128:131], v[208:211], v[96:99]
	v_mfma_f32_16x16x32_bf16 v[92:95], v[136:139], v[208:211], v[92:95]
	v_mfma_f32_16x16x32_bf16 v[80:83], v[128:131], v[216:219], v[80:83]
	v_mfma_f32_16x16x32_bf16 v[76:79], v[136:139], v[216:219], v[76:79]
	v_mfma_f32_16x16x32_bf16 v[124:127], v[132:135], v[196:199], v[124:127]
	v_mfma_f32_16x16x32_bf16 v[120:123], v[140:143], v[196:199], v[120:123]
	v_mfma_f32_16x16x32_bf16 v[112:115], v[132:135], v[204:207], v[112:115]
	v_mfma_f32_16x16x32_bf16 v[108:111], v[140:143], v[204:207], v[108:111]
	v_mfma_f32_16x16x32_bf16 v[96:99], v[132:135], v[212:215], v[96:99]
	v_mfma_f32_16x16x32_bf16 v[92:95], v[140:143], v[212:215], v[92:95]
	v_mfma_f32_16x16x32_bf16 v[80:83], v[132:135], v[220:223], v[80:83]
	v_mfma_f32_16x16x32_bf16 v[76:79], v[140:143], v[220:223], v[76:79]
	v_mfma_f32_16x16x32_bf16 v[116:119], v[172:175], v[188:191], v[116:119]
	v_mfma_f32_16x16x32_bf16 v[104:107], v[180:183], v[188:191], v[104:107]
	v_mfma_f32_16x16x32_bf16 v[100:103], v[172:175], v[200:203], v[100:103]
	v_mfma_f32_16x16x32_bf16 v[88:91], v[180:183], v[200:203], v[88:91]
	v_mfma_f32_16x16x32_bf16 v[84:87], v[172:175], v[208:211], v[84:87]
	v_mfma_f32_16x16x32_bf16 v[72:75], v[180:183], v[208:211], v[72:75]
	v_mfma_f32_16x16x32_bf16 v[68:71], v[172:175], v[216:219], v[68:71]
	v_mfma_f32_16x16x32_bf16 v[64:67], v[180:183], v[216:219], v[64:67]
	v_mfma_f32_16x16x32_bf16 v[116:119], v[176:179], v[196:199], v[116:119]
	v_mfma_f32_16x16x32_bf16 v[104:107], v[184:187], v[196:199], v[104:107]
	v_mfma_f32_16x16x32_bf16 v[100:103], v[176:179], v[204:207], v[100:103]
	v_mfma_f32_16x16x32_bf16 v[88:91], v[184:187], v[204:207], v[88:91]
	v_mfma_f32_16x16x32_bf16 v[84:87], v[176:179], v[212:215], v[84:87]
	v_mfma_f32_16x16x32_bf16 v[72:75], v[184:187], v[212:215], v[72:75]
	v_mfma_f32_16x16x32_bf16 v[68:71], v[176:179], v[220:223], v[68:71]
	v_mfma_f32_16x16x32_bf16 v[64:67], v[184:187], v[220:223], v[64:67]
	s_setprio 0
	s_barrier
	s_add_i32 s65, s56, s33
	v_lshl_add_u64 v[156:157], s[42:43], 0, v[146:147]
	s_mov_b32 m0, s65
	ds_read_b128 v[188:191], v170 offset:16384
	ds_read_b128 v[196:199], v170 offset:17408
	ds_read_b128 v[200:203], v170 offset:18432
	ds_read_b128 v[204:207], v170 offset:19456
	ds_read_b128 v[208:211], v170 offset:20480
	ds_read_b128 v[212:215], v170 offset:21504
	ds_read_b128 v[216:219], v170 offset:22528
	ds_read_b128 v[220:223], v170 offset:23552
	global_load_lds_dwordx4 v[156:157], off
	s_add_i32 m0, s65, 0x2000
	s_add_u32 s66, s42, 0x80000
	v_lshl_add_u64 v[192:193], s[42:43], 0, v[144:145]
	s_addc_u32 s67, s43, 0
	s_add_i32 s65, s54, s33
	global_load_lds_dwordx4 v[192:193], off
	v_lshl_add_u64 v[224:225], s[66:67], 0, v[146:147]
	s_mov_b32 m0, s65
	v_lshl_add_u64 v[226:227], s[44:45], 0, v[144:145]
	global_load_lds_dwordx4 v[224:225], off
	v_lshl_add_u64 v[224:225], s[66:67], 0, v[144:145]
	s_add_i32 m0, s65, 0x2000
	s_nop 0
	global_load_lds_dwordx4 v[224:225], off
	v_lshl_add_u64 v[224:225], s[44:45], 0, v[146:147]
	s_mov_b32 m0, s39
	s_nop 0
	global_load_lds_dwordx4 v[224:225], off
	s_mov_b32 m0, s46
	s_nop 0
	global_load_lds_dwordx4 v[226:227], off
	s_waitcnt vmcnt(8)
	s_waitcnt lgkmcnt(0)
	s_barrier
; #define PG8_STAGE(bufoff, gbase, voff) do { _Pragma("unroll") for (int _i = 0; _i < 2; ++_i) \
;         __builtin_amdgcn_global_load_lds((const unsigned*)((const char*)(gbase) + (voff)[_i]), (PG8_LAS unsigned*)(lds + (bufoff) + ldsw + _i * 8192), 16, 0, 0); } while (0)
; #define PG8_LDA(dst, b, h) do { _Pragma("unroll") for (int m = 0; m < 4; ++m) _Pragma("unroll") for (int k = 0; k < 2; ++k) dst[m][k] = *(const PG8_LAS bf16x8*)(lds + PG8_SA(b, h) + aoff + m * 2048 + k * 1024); } while (0)
; #define PG8_LDB(dst, b, h) do { _Pragma("unroll") for (int n = 0; n < 2; ++n) _Pragma("unroll") for (int k = 0; k < 2; ++k) dst[n][k] = *(const PG8_LAS bf16x8*)(lds + PG8_SB(b, h) + boff + n * 2048 + k * 1024); } while (0)
; #define PG8_MMA(ai, bj, At, Bt) do { __builtin_amdgcn_s_setprio(1); _Pragma("unroll") for (int m = 0; m < 4; ++m) _Pragma("unroll") for (int n = 0; n < 2; ++n) _Pragma("unroll") for (int k = 0; k < 2; ++k) \
;         acc[ai][bj][m][n] = __builtin_amdgcn_mfma_f32_16x16x32_bf16(Bt[n][k], At[m][k], acc[ai][bj][m][n], 0, 0, 0); __builtin_amdgcn_s_setprio(0); } while (0)
; #define PG8_WAIT_V(n) asm volatile("s_waitcnt vmcnt(" #n ")" ::: "memory")
; #define PG8_WAIT_L(n) asm volatile("s_waitcnt lgkmcnt(" #n ")" ::: "memory")
; #define PG8_BAR __builtin_amdgcn_s_barrier()
; #define PG8_SCHED __builtin_amdgcn_sched_barrier(0)
; template <class Epi, class Sched, bool ALIGN_EPI = false, bool SP2 = false>
; __device__ __forceinline__ void gemm_phase(PG8_LAS unsigned char* lds, const Gemm g, const Sched& S, const Epi& E) {
;     ...
;             PG8_WAIT_V(8); PG8_WAIT_L(0); PG8_BAR; PG8_MMA(1, 0, At, B0); PG8_MMA(1, 1, At, B1); PG8_BAR; PG8_SCHED;
;             PG8_LDB(B0, 1, 0); PG8_LDB(B1, 1, 1); PG8_SCHED; PG8_LDA(At, 1, 0); PG8_STAGE(PG8_SA(0, 1), a2 + hstepA, voffA);
;             PG8_WAIT_V(8); PG8_WAIT_L(0); PG8_BAR; PG8_MMA(0, 0, At, B0); PG8_MMA(0, 1, At, B1); PG8_BAR; PG8_SCHED;
	s_setprio 1
	s_waitcnt lgkmcnt(0)
	v_mfma_f32_16x16x32_bf16 v[60:63], v[128:131], v[188:191], v[60:63]
	v_mfma_f32_16x16x32_bf16 v[56:59], v[136:139], v[188:191], v[56:59]
	v_mfma_f32_16x16x32_bf16 v[48:51], v[128:131], v[200:203], v[48:51]
	v_mfma_f32_16x16x32_bf16 v[44:47], v[136:139], v[200:203], v[44:47]
	v_mfma_f32_16x16x32_bf16 v[32:35], v[128:131], v[208:211], v[32:35]
	v_mfma_f32_16x16x32_bf16 v[28:31], v[136:139], v[208:211], v[28:31]
	v_mfma_f32_16x16x32_bf16 v[16:19], v[128:131], v[216:219], v[16:19]
	v_mfma_f32_16x16x32_bf16 v[12:15], v[136:139], v[216:219], v[12:15]
	v_mfma_f32_16x16x32_bf16 v[60:63], v[132:135], v[196:199], v[60:63]
	v_mfma_f32_16x16x32_bf16 v[56:59], v[140:143], v[196:199], v[56:59]
	v_mfma_f32_16x16x32_bf16 v[48:51], v[132:135], v[204:207], v[48:51]
	v_mfma_f32_16x16x32_bf16 v[44:47], v[140:143], v[204:207], v[44:47]
	v_mfma_f32_16x16x32_bf16 v[32:35], v[132:135], v[212:215], v[32:35]
	v_mfma_f32_16x16x32_bf16 v[28:31], v[140:143], v[212:215], v[28:31]
	v_mfma_f32_16x16x32_bf16 v[16:19], v[132:135], v[220:223], v[16:19]
	v_mfma_f32_16x16x32_bf16 v[12:15], v[140:143], v[220:223], v[12:15]
	v_mfma_f32_16x16x32_bf16 v[52:55], v[172:175], v[188:191], v[52:55]
	v_mfma_f32_16x16x32_bf16 v[40:43], v[180:183], v[188:191], v[40:43]
	v_mfma_f32_16x16x32_bf16 v[36:39], v[172:175], v[200:203], v[36:39]
	v_mfma_f32_16x16x32_bf16 v[24:27], v[180:183], v[200:203], v[24:27]
	v_mfma_f32_16x16x32_bf16 v[20:23], v[172:175], v[208:211], v[20:23]
	v_mfma_f32_16x16x32_bf16 v[8:11], v[180:183], v[208:211], v[8:11]
	v_mfma_f32_16x16x32_bf16 v[4:7], v[172:175], v[216:219], v[4:7]
	v_mfma_f32_16x16x32_bf16 v[0:3], v[180:183], v[216:219], v[0:3]
	v_mfma_f32_16x16x32_bf16 v[52:55], v[176:179], v[196:199], v[52:55]
	v_mfma_f32_16x16x32_bf16 v[40:43], v[184:187], v[196:199], v[40:43]
	v_mfma_f32_16x16x32_bf16 v[36:39], v[176:179], v[204:207], v[36:39]
	v_mfma_f32_16x16x32_bf16 v[24:27], v[184:187], v[204:207], v[24:27]
	v_mfma_f32_16x16x32_bf16 v[20:23], v[176:179], v[212:215], v[20:23]
	v_mfma_f32_16x16x32_bf16 v[8:11], v[184:187], v[212:215], v[8:11]
	v_mfma_f32_16x16x32_bf16 v[4:7], v[176:179], v[220:223], v[4:7]
	v_mfma_f32_16x16x32_bf16 v[0:3], v[184:187], v[220:223], v[0:3]
	s_setprio 0
	s_barrier
	s_add_i32 s65, 0, 0x18000
	s_add_i32 s66, 0, 0x1c000
	v_add_u32_e32 v140, s65, v159
	v_add_u32_e32 v171, s66, v159
	ds_read_b128 v[128:131], v140
	ds_read_b128 v[132:135], v140 offset:1024
	ds_read_b128 v[136:139], v140 offset:2048
	ds_read_b128 v[140:143], v140 offset:3072
	ds_read_b128 v[172:175], v171
	ds_read_b128 v[176:179], v171 offset:1024
	ds_read_b128 v[180:183], v171 offset:2048
	ds_read_b128 v[184:187], v171 offset:3072
	s_add_u32 s44, s44, 0x80000
	s_addc_u32 s45, s45, 0
	s_mov_b32 m0, s47
	v_lshl_add_u64 v[228:229], s[44:45], 0, v[146:147]
	ds_read_b128 v[188:191], v170 offset:32768
	ds_read_b128 v[196:199], v170 offset:33792
	ds_read_b128 v[200:203], v170 offset:34816
	ds_read_b128 v[204:207], v170 offset:35840
	ds_read_b128 v[208:211], v170 offset:36864
	ds_read_b128 v[212:215], v170 offset:37888
	ds_read_b128 v[216:219], v170 offset:38912
	ds_read_b128 v[220:223], v170 offset:39936
	global_load_lds_dwordx4 v[228:229], off
	v_lshl_add_u64 v[228:229], s[44:45], 0, v[144:145]
	s_mov_b32 m0, s48
	s_nop 0
	global_load_lds_dwordx4 v[228:229], off
	s_waitcnt vmcnt(8)
	s_waitcnt lgkmcnt(0)
	s_barrier
	s_setprio 1
	s_waitcnt lgkmcnt(0)
	v_mfma_f32_16x16x32_bf16 v[124:127], v[128:131], v[188:191], v[124:127]
	v_mfma_f32_16x16x32_bf16 v[120:123], v[136:139], v[188:191], v[120:123]
	v_mfma_f32_16x16x32_bf16 v[112:115], v[128:131], v[200:203], v[112:115]
	v_mfma_f32_16x16x32_bf16 v[108:111], v[136:139], v[200:203], v[108:111]
	v_mfma_f32_16x16x32_bf16 v[96:99], v[128:131], v[208:211], v[96:99]
	v_mfma_f32_16x16x32_bf16 v[92:95], v[136:139], v[208:211], v[92:95]
	v_mfma_f32_16x16x32_bf16 v[80:83], v[128:131], v[216:219], v[80:83]
	v_mfma_f32_16x16x32_bf16 v[76:79], v[136:139], v[216:219], v[76:79]
	v_mfma_f32_16x16x32_bf16 v[124:127], v[132:135], v[196:199], v[124:127]
	v_mfma_f32_16x16x32_bf16 v[120:123], v[140:143], v[196:199], v[120:123]
	v_mfma_f32_16x16x32_bf16 v[112:115], v[132:135], v[204:207], v[112:115]
	v_mfma_f32_16x16x32_bf16 v[108:111], v[140:143], v[204:207], v[108:111]
	v_mfma_f32_16x16x32_bf16 v[96:99], v[132:135], v[212:215], v[96:99]
	v_mfma_f32_16x16x32_bf16 v[92:95], v[140:143], v[212:215], v[92:95]
	v_mfma_f32_16x16x32_bf16 v[80:83], v[132:135], v[220:223], v[80:83]
	v_mfma_f32_16x16x32_bf16 v[76:79], v[140:143], v[220:223], v[76:79]
	v_mfma_f32_16x16x32_bf16 v[116:119], v[172:175], v[188:191], v[116:119]
	v_mfma_f32_16x16x32_bf16 v[104:107], v[180:183], v[188:191], v[104:107]
	v_mfma_f32_16x16x32_bf16 v[100:103], v[172:175], v[200:203], v[100:103]
	v_mfma_f32_16x16x32_bf16 v[88:91], v[180:183], v[200:203], v[88:91]
	v_mfma_f32_16x16x32_bf16 v[84:87], v[172:175], v[208:211], v[84:87]
	v_mfma_f32_16x16x32_bf16 v[72:75], v[180:183], v[208:211], v[72:75]
	v_mfma_f32_16x16x32_bf16 v[68:71], v[172:175], v[216:219], v[68:71]
	v_mfma_f32_16x16x32_bf16 v[64:67], v[180:183], v[216:219], v[64:67]
	v_mfma_f32_16x16x32_bf16 v[116:119], v[176:179], v[196:199], v[116:119]
	v_mfma_f32_16x16x32_bf16 v[104:107], v[184:187], v[196:199], v[104:107]
	v_mfma_f32_16x16x32_bf16 v[100:103], v[176:179], v[204:207], v[100:103]
	v_mfma_f32_16x16x32_bf16 v[88:91], v[184:187], v[204:207], v[88:91]
	v_mfma_f32_16x16x32_bf16 v[84:87], v[176:179], v[212:215], v[84:87]
	v_mfma_f32_16x16x32_bf16 v[72:75], v[184:187], v[212:215], v[72:75]
	v_mfma_f32_16x16x32_bf16 v[68:71], v[176:179], v[220:223], v[68:71]
	v_mfma_f32_16x16x32_bf16 v[64:67], v[184:187], v[220:223], v[64:67]
	s_setprio 0
	s_barrier
; #define PG8_STAGE(bufoff, gbase, voff) do { _Pragma("unroll") for (int _i = 0; _i < 2; ++_i) \
;         __builtin_amdgcn_global_load_lds((const unsigned*)((const char*)(gbase) + (voff)[_i]), (PG8_LAS unsigned*)(lds + (bufoff) + ldsw + _i * 8192), 16, 0, 0); } while (0)
; #define PG8_LDA(dst, b, h) do { _Pragma("unroll") for (int m = 0; m < 4; ++m) _Pragma("unroll") for (int k = 0; k < 2; ++k) dst[m][k] = *(const PG8_LAS bf16x8*)(lds + PG8_SA(b, h) + aoff + m * 2048 + k * 1024); } while (0)
; #define PG8_WAIT_V(n) asm volatile("s_waitcnt vmcnt(" #n ")" ::: "memory")
; #define PG8_WAIT_L(n) asm volatile("s_waitcnt lgkmcnt(" #n ")" ::: "memory")
; template <class Epi, class Sched, bool ALIGN_EPI = false, bool SP2 = false>
; __device__ __forceinline__ void gemm_phase(PG8_LAS unsigned char* lds, const Gemm g, const Sched& S, const Epi& E) {
;     ...
;         for (int t = 0; t < nt; t += 2) {
;             const bool last = (t == nt - 2);
;             const char* a1 = cA + (size_t)(t + 1) * kstep;
;             const char* a2 = last ? nA : cA + (size_t)(t + 2) * kstep; const char* b2 = last ? nB : cB + (size_t)(t + 2) * kstep;
;             const char* a3 = a2 + kstep; const char* b3 = b2 + kstep;
;             if (last && has_next) S.a_ready(nxt);
;             if constexpr (SP2) {
;             PG8_LDB(B0, 0, 0); PG8_LDB(B1, 0, 1); PG8_SCHED; PG8_LDA(At, 0, 0); PG8_STAGE(PG8_SA(1, 1), a1 + hstepA, voffA);
;             PG8_WAIT_V(8); PG8_WAIT_L(0); PG8_BAR; PG8_MMA(0, 0, At, B0); PG8_MMA(0, 1, At, B1); PG8_BAR; PG8_SCHED;
;             PG8_LDA(At, 0, 1); PG8_STAGE(PG8_SB(0, 0), b2, voffB); PG8_STAGE(PG8_SB(0, 1), b2 + hstepB, voffB); PG8_STAGE(PG8_SA(0, 0), a2, voffA);
;             PG8_WAIT_V(8); PG8_WAIT_L(0); PG8_BAR; PG8_MMA(1, 0, At, B0); PG8_MMA(1, 1, At, B1); PG8_BAR; PG8_SCHED;
;             PG8_LDB(B0, 1, 0); PG8_LDB(B1, 1, 1); PG8_SCHED; PG8_LDA(At, 1, 0); PG8_STAGE(PG8_SA(0, 1), a2 + hstepA, voffA);
;             PG8_WAIT_V(8); PG8_WAIT_L(0); PG8_BAR; PG8_MMA(0, 0, At, B0); PG8_MMA(0, 1, At, B1); PG8_BAR; PG8_SCHED;
;             PG8_LDA(At, 1, 1); PG8_STAGE(PG8_SB(1, 0), b3, voffB); PG8_STAGE(PG8_SB(1, 1), b3 + hstepB, voffB); PG8_STAGE(PG8_SA(1, 0), a3, voffA);
;             PG8_WAIT_V(8); PG8_WAIT_L(0); PG8_BAR; PG8_MMA(1, 0, At, B0); PG8_MMA(1, 1, At, B1); PG8_BAR; PG8_SCHED;
;     ...
;         if constexpr (ALIGN_EPI) { if (wr == 0) PG8_BAR; }
	s_add_i32 s44, s65, s33
	v_lshl_add_u64 v[156:157], v[156:157], 0, s[10:11]
	s_mov_b32 m0, s44
	ds_read_b128 v[188:191], v170 offset:49152
	ds_read_b128 v[196:199], v170 offset:50176
	ds_read_b128 v[200:203], v170 offset:51200
	ds_read_b128 v[204:207], v170 offset:52224
	ds_read_b128 v[208:211], v170 offset:53248
	ds_read_b128 v[212:215], v170 offset:54272
	ds_read_b128 v[216:219], v170 offset:55296
	ds_read_b128 v[220:223], v170 offset:56320
	global_load_lds_dwordx4 v[156:157], off
	s_add_i32 m0, s44, 0x2000
	s_add_u32 s42, s42, 0x80080
	v_lshl_add_u64 v[156:157], v[192:193], 0, s[10:11]
	s_addc_u32 s43, s43, 0
	s_add_i32 s44, s66, s33
	global_load_lds_dwordx4 v[156:157], off
	v_lshl_add_u64 v[156:157], s[42:43], 0, v[146:147]
	s_mov_b32 m0, s44
	s_nop 0
	global_load_lds_dwordx4 v[156:157], off
	v_lshl_add_u64 v[156:157], s[42:43], 0, v[144:145]
	s_add_i32 m0, s44, 0x2000
	s_nop 0
	global_load_lds_dwordx4 v[156:157], off
	v_lshl_add_u64 v[156:157], v[224:225], 0, s[10:11]
	s_mov_b32 m0, s52
	s_nop 0
	global_load_lds_dwordx4 v[156:157], off
	v_lshl_add_u64 v[156:157], v[226:227], 0, s[10:11]
	s_mov_b32 m0, s53
	s_nop 0
	global_load_lds_dwordx4 v[156:157], off
	s_waitcnt vmcnt(8)
	s_waitcnt lgkmcnt(0)
	s_barrier
	s_setprio 1
	s_waitcnt lgkmcnt(0)
	v_mfma_f32_16x16x32_bf16 v[60:63], v[128:131], v[188:191], v[60:63]
	v_mfma_f32_16x16x32_bf16 v[56:59], v[136:139], v[188:191], v[56:59]
	v_mfma_f32_16x16x32_bf16 v[48:51], v[128:131], v[200:203], v[48:51]
	v_mfma_f32_16x16x32_bf16 v[44:47], v[136:139], v[200:203], v[44:47]
	v_mfma_f32_16x16x32_bf16 v[32:35], v[128:131], v[208:211], v[32:35]
	v_mfma_f32_16x16x32_bf16 v[28:31], v[136:139], v[208:211], v[28:31]
	v_mfma_f32_16x16x32_bf16 v[16:19], v[128:131], v[216:219], v[16:19]
	v_mfma_f32_16x16x32_bf16 v[12:15], v[136:139], v[216:219], v[12:15]
	v_mfma_f32_16x16x32_bf16 v[60:63], v[132:135], v[196:199], v[60:63]
	v_mfma_f32_16x16x32_bf16 v[56:59], v[140:143], v[196:199], v[56:59]
	v_mfma_f32_16x16x32_bf16 v[48:51], v[132:135], v[204:207], v[48:51]
	v_mfma_f32_16x16x32_bf16 v[44:47], v[140:143], v[204:207], v[44:47]
	v_mfma_f32_16x16x32_bf16 v[32:35], v[132:135], v[212:215], v[32:35]
	v_mfma_f32_16x16x32_bf16 v[28:31], v[140:143], v[212:215], v[28:31]
	v_mfma_f32_16x16x32_bf16 v[16:19], v[132:135], v[220:223], v[16:19]
	v_mfma_f32_16x16x32_bf16 v[12:15], v[140:143], v[220:223], v[12:15]
	v_mfma_f32_16x16x32_bf16 v[52:55], v[172:175], v[188:191], v[52:55]
	v_mfma_f32_16x16x32_bf16 v[40:43], v[180:183], v[188:191], v[40:43]
	v_mfma_f32_16x16x32_bf16 v[36:39], v[172:175], v[200:203], v[36:39]
	v_mfma_f32_16x16x32_bf16 v[24:27], v[180:183], v[200:203], v[24:27]
	v_mfma_f32_16x16x32_bf16 v[20:23], v[172:175], v[208:211], v[20:23]
	v_mfma_f32_16x16x32_bf16 v[8:11], v[180:183], v[208:211], v[8:11]
	v_mfma_f32_16x16x32_bf16 v[4:7], v[172:175], v[216:219], v[4:7]
	v_mfma_f32_16x16x32_bf16 v[0:3], v[180:183], v[216:219], v[0:3]
	v_mfma_f32_16x16x32_bf16 v[52:55], v[176:179], v[196:199], v[52:55]
	v_mfma_f32_16x16x32_bf16 v[40:43], v[184:187], v[196:199], v[40:43]
	v_mfma_f32_16x16x32_bf16 v[36:39], v[176:179], v[204:207], v[36:39]
	v_mfma_f32_16x16x32_bf16 v[24:27], v[184:187], v[204:207], v[24:27]
	v_mfma_f32_16x16x32_bf16 v[20:23], v[176:179], v[212:215], v[20:23]
	v_mfma_f32_16x16x32_bf16 v[8:11], v[184:187], v[212:215], v[8:11]
	v_mfma_f32_16x16x32_bf16 v[4:7], v[176:179], v[220:223], v[4:7]
	v_mfma_f32_16x16x32_bf16 v[0:3], v[184:187], v[220:223], v[0:3]
	s_setprio 0
	s_barrier
	s_add_i32 s64, s64, 2
	s_add_u32 s40, s40, 0x100
	s_addc_u32 s41, s41, 0
	s_add_u32 s62, s62, 0x100
	s_addc_u32 s63, s63, 0
	s_cmp_gt_u32 s64, 29
	s_cbranch_scc0 .LBB0_613
	s_and_b64 vcc, exec, s[18:19]
	s_cbranch_vccz .LBB0_616
	s_barrier

; #define PG8_STAGE(bufoff, gbase, voff) do { _Pragma("unroll") for (int _i = 0; _i < 2; ++_i) \
;         __builtin_amdgcn_global_load_lds((const unsigned*)((const char*)(gbase) + (voff)[_i]), (PG8_LAS unsigned*)(lds + (bufoff) + ldsw + _i * 8192), 16, 0, 0); } while (0)
; #define PG8_LDA(dst, b, h) do { _Pragma("unroll") for (int m = 0; m < 4; ++m) _Pragma("unroll") for (int k = 0; k < 2; ++k) dst[m][k] = *(const PG8_LAS bf16x8*)(lds + PG8_SA(b, h) + aoff + m * 2048 + k * 1024); } while (0)
; #define PG8_LDB(dst, b, h) do { _Pragma("unroll") for (int n = 0; n < 2; ++n) _Pragma("unroll") for (int k = 0; k < 2; ++k) dst[n][k] = *(const PG8_LAS bf16x8*)(lds + PG8_SB(b, h) + boff + n * 2048 + k * 1024); } while (0)
; #define PG8_MMA(ai, bj, At, Bt) do { __builtin_amdgcn_s_setprio(1); _Pragma("unroll") for (int m = 0; m < 4; ++m) _Pragma("unroll") for (int n = 0; n < 2; ++n) _Pragma("unroll") for (int k = 0; k < 2; ++k) \
;         acc[ai][bj][m][n] = __builtin_amdgcn_mfma_f32_16x16x32_bf16(Bt[n][k], At[m][k], acc[ai][bj][m][n], 0, 0, 0); __builtin_amdgcn_s_setprio(0); } while (0)
; #define PG8_WAIT_V(n) asm volatile("s_waitcnt vmcnt(" #n ")" ::: "memory")
; #define PG8_WAIT_L(n) asm volatile("s_waitcnt lgkmcnt(" #n ")" ::: "memory")
; #define PG8_BAR __builtin_amdgcn_s_barrier()
; #define PG8_SCHED __builtin_amdgcn_sched_barrier(0)
; template <class Epi, class Sched, bool ALIGN_EPI = false, bool SP2 = false>
; __device__ __forceinline__ void gemm_phase(PG8_LAS unsigned char* lds, const Gemm g, const Sched& S, const Epi& E) {
;     ...
;             const bool last = (t == nt - 2);
;             const char* a1 = cA + (size_t)(t + 1) * kstep;
;             const char* a2 = last ? nA : cA + (size_t)(t + 2) * kstep; const char* b2 = last ? nB : cB + (size_t)(t + 2) * kstep;
;             const char* a3 = a2 + kstep; const char* b3 = b2 + kstep;
;             if (last && has_next) S.a_ready(nxt);
;             if constexpr (SP2) {
;             PG8_LDB(B0, 0, 0); PG8_LDB(B1, 0, 1); PG8_SCHED; PG8_LDA(At, 0, 0); PG8_STAGE(PG8_SA(1, 1), a1 + hstepA, voffA);
;             PG8_WAIT_V(8); PG8_WAIT_L(0); PG8_BAR; PG8_MMA(0, 0, At, B0); PG8_MMA(0, 1, At, B1); PG8_BAR; PG8_SCHED;
;             PG8_LDA(At, 0, 1); PG8_STAGE(PG8_SB(0, 0), b2, voffB); PG8_STAGE(PG8_SB(0, 1), b2 + hstepB, voffB); PG8_STAGE(PG8_SA(0, 0), a2, voffA);
.LBB0_736:
	s_add_u32 s34, s65, s30
	s_addc_u32 s35, s66, s31
	s_add_u32 s34, s34, 0x5b00100
	s_addc_u32 s35, s35, 0
	s_add_u32 s70, s67, s30
	s_addc_u32 s71, s68, s31
	s_cmpk_eq_i32 s30, 0xf00
	s_cselect_b32 s37, s29, s35
	s_cselect_b32 s36, s28, s34
	v_add_u32_e32 v169, s56, v148
	s_cselect_b32 s35, s5, s71
	s_cselect_b32 s34, s4, s70
	s_add_i32 s72, 0, 0x14000
	ds_read_b128 v[150:153], v169
	ds_read_b128 v[154:157], v169 offset:1024
	ds_read_b128 v[158:161], v169 offset:2048
	ds_read_b128 v[170:173], v169 offset:3072
	v_add_u32_e32 v169, s72, v148
	ds_read_b128 v[174:177], v169
	ds_read_b128 v[178:181], v169 offset:1024
	ds_read_b128 v[182:185], v169 offset:2048
	ds_read_b128 v[186:189], v169 offset:3072
	v_lshl_add_u64 v[224:225], v[140:141], 0, s[30:31]
	s_add_i32 m0, s3, 0xc000
	ds_read_b128 v[190:193], v149
	ds_read_b128 v[196:199], v149 offset:1024
	ds_read_b128 v[200:203], v149 offset:2048
	ds_read_b128 v[204:207], v149 offset:3072
	ds_read_b128 v[208:211], v149 offset:4096
	ds_read_b128 v[212:215], v149 offset:5120
	ds_read_b128 v[216:219], v149 offset:6144
	ds_read_b128 v[220:223], v149 offset:7168
	global_load_lds_dwordx4 v[224:225], off
	v_lshl_add_u64 v[224:225], v[142:143], 0, s[30:31]
	s_add_i32 m0, s3, 0xe000
	s_nop 0
	global_load_lds_dwordx4 v[224:225], off
	s_waitcnt vmcnt(8)
	s_waitcnt lgkmcnt(0)
	s_barrier
	s_setprio 1
	s_waitcnt lgkmcnt(0)
	v_mfma_f32_16x16x32_bf16 v[124:127], v[150:153], v[190:193], v[124:127]
	v_mfma_f32_16x16x32_bf16 v[120:123], v[158:161], v[190:193], v[120:123]
	v_mfma_f32_16x16x32_bf16 v[116:119], v[150:153], v[200:203], v[116:119]
	v_mfma_f32_16x16x32_bf16 v[112:115], v[158:161], v[200:203], v[112:115]
	v_mfma_f32_16x16x32_bf16 v[100:103], v[150:153], v[208:211], v[100:103]
	v_mfma_f32_16x16x32_bf16 v[96:99], v[158:161], v[208:211], v[96:99]
	v_mfma_f32_16x16x32_bf16 v[84:87], v[150:153], v[216:219], v[84:87]
	v_mfma_f32_16x16x32_bf16 v[80:83], v[158:161], v[216:219], v[80:83]
	v_mfma_f32_16x16x32_bf16 v[124:127], v[154:157], v[196:199], v[124:127]
	v_mfma_f32_16x16x32_bf16 v[120:123], v[170:173], v[196:199], v[120:123]
	v_mfma_f32_16x16x32_bf16 v[116:119], v[154:157], v[204:207], v[116:119]
	v_mfma_f32_16x16x32_bf16 v[112:115], v[170:173], v[204:207], v[112:115]
	v_mfma_f32_16x16x32_bf16 v[100:103], v[154:157], v[212:215], v[100:103]
	v_mfma_f32_16x16x32_bf16 v[96:99], v[170:173], v[212:215], v[96:99]
	v_mfma_f32_16x16x32_bf16 v[84:87], v[154:157], v[220:223], v[84:87]
	v_mfma_f32_16x16x32_bf16 v[80:83], v[170:173], v[220:223], v[80:83]
	v_mfma_f32_16x16x32_bf16 v[108:111], v[174:177], v[190:193], v[108:111]
	v_mfma_f32_16x16x32_bf16 v[104:107], v[182:185], v[190:193], v[104:107]
	v_mfma_f32_16x16x32_bf16 v[92:95], v[174:177], v[200:203], v[92:95]
	v_mfma_f32_16x16x32_bf16 v[88:91], v[182:185], v[200:203], v[88:91]
	v_mfma_f32_16x16x32_bf16 v[76:79], v[174:177], v[208:211], v[76:79]
	v_mfma_f32_16x16x32_bf16 v[72:75], v[182:185], v[208:211], v[72:75]
	v_mfma_f32_16x16x32_bf16 v[68:71], v[174:177], v[216:219], v[68:71]
	v_mfma_f32_16x16x32_bf16 v[64:67], v[182:185], v[216:219], v[64:67]
	v_mfma_f32_16x16x32_bf16 v[108:111], v[178:181], v[196:199], v[108:111]
	v_mfma_f32_16x16x32_bf16 v[104:107], v[186:189], v[196:199], v[104:107]
	v_mfma_f32_16x16x32_bf16 v[92:95], v[178:181], v[204:207], v[92:95]
	v_mfma_f32_16x16x32_bf16 v[88:91], v[186:189], v[204:207], v[88:91]
	v_mfma_f32_16x16x32_bf16 v[76:79], v[178:181], v[212:215], v[76:79]
	v_mfma_f32_16x16x32_bf16 v[72:75], v[186:189], v[212:215], v[72:75]
	v_mfma_f32_16x16x32_bf16 v[68:71], v[178:181], v[220:223], v[68:71]
	v_mfma_f32_16x16x32_bf16 v[64:67], v[186:189], v[220:223], v[64:67]
	s_setprio 0
	s_barrier
	s_add_i32 s70, s56, s2
	v_lshl_add_u64 v[224:225], s[34:35], 0, v[132:133]
	s_mov_b32 m0, s70
	ds_read_b128 v[190:193], v149 offset:16384
	ds_read_b128 v[196:199], v149 offset:17408
	ds_read_b128 v[200:203], v149 offset:18432
	ds_read_b128 v[204:207], v149 offset:19456
	ds_read_b128 v[208:211], v149 offset:20480
	ds_read_b128 v[212:215], v149 offset:21504
	ds_read_b128 v[216:219], v149 offset:22528
	ds_read_b128 v[220:223], v149 offset:23552
	global_load_lds_dwordx4 v[224:225], off
	s_add_i32 m0, s70, 0x2000
	s_add_u32 s70, s34, 0x80000
	v_lshl_add_u64 v[226:227], s[34:35], 0, v[138:139]
	s_addc_u32 s71, s35, 0
	s_add_i32 s72, s72, s2
	global_load_lds_dwordx4 v[226:227], off
	v_lshl_add_u64 v[228:229], s[70:71], 0, v[132:133]
	s_mov_b32 m0, s72
	v_lshl_add_u64 v[230:231], s[36:37], 0, v[136:137]
	global_load_lds_dwordx4 v[228:229], off
	v_lshl_add_u64 v[228:229], s[70:71], 0, v[138:139]
	s_add_i32 m0, s72, 0x2000
	s_nop 0
	global_load_lds_dwordx4 v[228:229], off
	v_lshl_add_u64 v[228:229], s[36:37], 0, v[134:135]
	s_mov_b32 m0, s3
	s_nop 0
	global_load_lds_dwordx4 v[228:229], off
	s_mov_b32 m0, s26
	s_nop 0
	global_load_lds_dwordx4 v[230:231], off
	s_waitcnt vmcnt(8)
	s_waitcnt lgkmcnt(0)
	s_barrier
; #define PG8_STAGE(bufoff, gbase, voff) do { _Pragma("unroll") for (int _i = 0; _i < 2; ++_i) \
;         __builtin_amdgcn_global_load_lds((const unsigned*)((const char*)(gbase) + (voff)[_i]), (PG8_LAS unsigned*)(lds + (bufoff) + ldsw + _i * 8192), 16, 0, 0); } while (0)
; #define PG8_LDA(dst, b, h) do { _Pragma("unroll") for (int m = 0; m < 4; ++m) _Pragma("unroll") for (int k = 0; k < 2; ++k) dst[m][k] = *(const PG8_LAS bf16x8*)(lds + PG8_SA(b, h) + aoff + m * 2048 + k * 1024); } while (0)
; #define PG8_LDB(dst, b, h) do { _Pragma("unroll") for (int n = 0; n < 2; ++n) _Pragma("unroll") for (int k = 0; k < 2; ++k) dst[n][k] = *(const PG8_LAS bf16x8*)(lds + PG8_SB(b, h) + boff + n * 2048 + k * 1024); } while (0)
; #define PG8_MMA(ai, bj, At, Bt) do { __builtin_amdgcn_s_setprio(1); _Pragma("unroll") for (int m = 0; m < 4; ++m) _Pragma("unroll") for (int n = 0; n < 2; ++n) _Pragma("unroll") for (int k = 0; k < 2; ++k) \
;         acc[ai][bj][m][n] = __builtin_amdgcn_mfma_f32_16x16x32_bf16(Bt[n][k], At[m][k], acc[ai][bj][m][n], 0, 0, 0); __builtin_amdgcn_s_setprio(0); } while (0)
; #define PG8_WAIT_V(n) asm volatile("s_waitcnt vmcnt(" #n ")" ::: "memory")
; #define PG8_WAIT_L(n) asm volatile("s_waitcnt lgkmcnt(" #n ")" ::: "memory")
; #define PG8_BAR __builtin_amdgcn_s_barrier()
; #define PG8_SCHED __builtin_amdgcn_sched_barrier(0)
; template <class Epi, class Sched, bool ALIGN_EPI = false, bool SP2 = false>
; __device__ __forceinline__ void gemm_phase(PG8_LAS unsigned char* lds, const Gemm g, const Sched& S, const Epi& E) {
;     ...
;             PG8_WAIT_V(8); PG8_WAIT_L(0); PG8_BAR; PG8_MMA(1, 0, At, B0); PG8_MMA(1, 1, At, B1); PG8_BAR; PG8_SCHED;
;             PG8_LDB(B0, 1, 0); PG8_LDB(B1, 1, 1); PG8_SCHED; PG8_LDA(At, 1, 0); PG8_STAGE(PG8_SA(0, 1), a2 + hstepA, voffA);
;             PG8_WAIT_V(8); PG8_WAIT_L(0); PG8_BAR; PG8_MMA(0, 0, At, B0); PG8_MMA(0, 1, At, B1); PG8_BAR; PG8_SCHED;
	s_setprio 1
	s_waitcnt lgkmcnt(0)
	v_mfma_f32_16x16x32_bf16 v[60:63], v[150:153], v[190:193], v[60:63]
	v_mfma_f32_16x16x32_bf16 v[56:59], v[158:161], v[190:193], v[56:59]
	v_mfma_f32_16x16x32_bf16 v[52:55], v[150:153], v[200:203], v[52:55]
	v_mfma_f32_16x16x32_bf16 v[48:51], v[158:161], v[200:203], v[48:51]
	v_mfma_f32_16x16x32_bf16 v[36:39], v[150:153], v[208:211], v[36:39]
	v_mfma_f32_16x16x32_bf16 v[32:35], v[158:161], v[208:211], v[32:35]
	v_mfma_f32_16x16x32_bf16 v[20:23], v[150:153], v[216:219], v[20:23]
	v_mfma_f32_16x16x32_bf16 v[16:19], v[158:161], v[216:219], v[16:19]
	v_mfma_f32_16x16x32_bf16 v[60:63], v[154:157], v[196:199], v[60:63]
	v_mfma_f32_16x16x32_bf16 v[56:59], v[170:173], v[196:199], v[56:59]
	v_mfma_f32_16x16x32_bf16 v[52:55], v[154:157], v[204:207], v[52:55]
	v_mfma_f32_16x16x32_bf16 v[48:51], v[170:173], v[204:207], v[48:51]
	v_mfma_f32_16x16x32_bf16 v[36:39], v[154:157], v[212:215], v[36:39]
	v_mfma_f32_16x16x32_bf16 v[32:35], v[170:173], v[212:215], v[32:35]
	v_mfma_f32_16x16x32_bf16 v[20:23], v[154:157], v[220:223], v[20:23]
	v_mfma_f32_16x16x32_bf16 v[16:19], v[170:173], v[220:223], v[16:19]
	v_mfma_f32_16x16x32_bf16 v[44:47], v[174:177], v[190:193], v[44:47]
	v_mfma_f32_16x16x32_bf16 v[40:43], v[182:185], v[190:193], v[40:43]
	v_mfma_f32_16x16x32_bf16 v[28:31], v[174:177], v[200:203], v[28:31]
	v_mfma_f32_16x16x32_bf16 v[24:27], v[182:185], v[200:203], v[24:27]
	v_mfma_f32_16x16x32_bf16 v[12:15], v[174:177], v[208:211], v[12:15]
	v_mfma_f32_16x16x32_bf16 v[8:11], v[182:185], v[208:211], v[8:11]
	v_mfma_f32_16x16x32_bf16 v[4:7], v[174:177], v[216:219], v[4:7]
	v_mfma_f32_16x16x32_bf16 v[0:3], v[182:185], v[216:219], v[0:3]
	v_mfma_f32_16x16x32_bf16 v[44:47], v[178:181], v[196:199], v[44:47]
	v_mfma_f32_16x16x32_bf16 v[40:43], v[186:189], v[196:199], v[40:43]
	v_mfma_f32_16x16x32_bf16 v[28:31], v[178:181], v[204:207], v[28:31]
	v_mfma_f32_16x16x32_bf16 v[24:27], v[186:189], v[204:207], v[24:27]
	v_mfma_f32_16x16x32_bf16 v[12:15], v[178:181], v[212:215], v[12:15]
	v_mfma_f32_16x16x32_bf16 v[8:11], v[186:189], v[212:215], v[8:11]
	v_mfma_f32_16x16x32_bf16 v[4:7], v[178:181], v[220:223], v[4:7]
	v_mfma_f32_16x16x32_bf16 v[0:3], v[186:189], v[220:223], v[0:3]
	s_setprio 0
	s_barrier
	s_add_i32 s70, 0, 0x18000
	v_add_u32_e32 v169, s70, v148
	s_add_i32 s71, 0, 0x1c000
	ds_read_b128 v[150:153], v169
	ds_read_b128 v[154:157], v169 offset:1024
	ds_read_b128 v[158:161], v169 offset:2048
	ds_read_b128 v[170:173], v169 offset:3072
	v_add_u32_e32 v169, s71, v148
	ds_read_b128 v[174:177], v169
	ds_read_b128 v[178:181], v169 offset:1024
	ds_read_b128 v[182:185], v169 offset:2048
	ds_read_b128 v[186:189], v169 offset:3072
	s_add_u32 s36, s36, 0x80000
	s_addc_u32 s37, s37, 0
	s_mov_b32 m0, s33
	v_lshl_add_u64 v[232:233], s[36:37], 0, v[134:135]
	ds_read_b128 v[190:193], v149 offset:32768
	ds_read_b128 v[196:199], v149 offset:33792
	ds_read_b128 v[200:203], v149 offset:34816
	ds_read_b128 v[204:207], v149 offset:35840
	ds_read_b128 v[208:211], v149 offset:36864
	ds_read_b128 v[212:215], v149 offset:37888
	ds_read_b128 v[216:219], v149 offset:38912
	ds_read_b128 v[220:223], v149 offset:39936
	global_load_lds_dwordx4 v[232:233], off
	v_lshl_add_u64 v[232:233], s[36:37], 0, v[136:137]
	s_mov_b32 m0, s61
	s_nop 0
	global_load_lds_dwordx4 v[232:233], off
	s_waitcnt vmcnt(8)
	s_waitcnt lgkmcnt(0)
	s_barrier
	s_setprio 1
	s_waitcnt lgkmcnt(0)
	v_mfma_f32_16x16x32_bf16 v[124:127], v[150:153], v[190:193], v[124:127]
	v_mfma_f32_16x16x32_bf16 v[120:123], v[158:161], v[190:193], v[120:123]
	v_mfma_f32_16x16x32_bf16 v[116:119], v[150:153], v[200:203], v[116:119]
	v_mfma_f32_16x16x32_bf16 v[112:115], v[158:161], v[200:203], v[112:115]
	v_mfma_f32_16x16x32_bf16 v[100:103], v[150:153], v[208:211], v[100:103]
	v_mfma_f32_16x16x32_bf16 v[96:99], v[158:161], v[208:211], v[96:99]
	v_mfma_f32_16x16x32_bf16 v[84:87], v[150:153], v[216:219], v[84:87]
	v_mfma_f32_16x16x32_bf16 v[80:83], v[158:161], v[216:219], v[80:83]
	v_mfma_f32_16x16x32_bf16 v[124:127], v[154:157], v[196:199], v[124:127]
	v_mfma_f32_16x16x32_bf16 v[120:123], v[170:173], v[196:199], v[120:123]
	v_mfma_f32_16x16x32_bf16 v[116:119], v[154:157], v[204:207], v[116:119]
	v_mfma_f32_16x16x32_bf16 v[112:115], v[170:173], v[204:207], v[112:115]
	v_mfma_f32_16x16x32_bf16 v[100:103], v[154:157], v[212:215], v[100:103]
	v_mfma_f32_16x16x32_bf16 v[96:99], v[170:173], v[212:215], v[96:99]
	v_mfma_f32_16x16x32_bf16 v[84:87], v[154:157], v[220:223], v[84:87]
	v_mfma_f32_16x16x32_bf16 v[80:83], v[170:173], v[220:223], v[80:83]
	v_mfma_f32_16x16x32_bf16 v[108:111], v[174:177], v[190:193], v[108:111]
	v_mfma_f32_16x16x32_bf16 v[104:107], v[182:185], v[190:193], v[104:107]
	v_mfma_f32_16x16x32_bf16 v[92:95], v[174:177], v[200:203], v[92:95]
	v_mfma_f32_16x16x32_bf16 v[88:91], v[182:185], v[200:203], v[88:91]
	v_mfma_f32_16x16x32_bf16 v[76:79], v[174:177], v[208:211], v[76:79]
	v_mfma_f32_16x16x32_bf16 v[72:75], v[182:185], v[208:211], v[72:75]
	v_mfma_f32_16x16x32_bf16 v[68:71], v[174:177], v[216:219], v[68:71]
	v_mfma_f32_16x16x32_bf16 v[64:67], v[182:185], v[216:219], v[64:67]
	v_mfma_f32_16x16x32_bf16 v[108:111], v[178:181], v[196:199], v[108:111]
	v_mfma_f32_16x16x32_bf16 v[104:107], v[186:189], v[196:199], v[104:107]
	v_mfma_f32_16x16x32_bf16 v[92:95], v[178:181], v[204:207], v[92:95]
	v_mfma_f32_16x16x32_bf16 v[88:91], v[186:189], v[204:207], v[88:91]
	v_mfma_f32_16x16x32_bf16 v[76:79], v[178:181], v[212:215], v[76:79]
	v_mfma_f32_16x16x32_bf16 v[72:75], v[186:189], v[212:215], v[72:75]
	v_mfma_f32_16x16x32_bf16 v[68:71], v[178:181], v[220:223], v[68:71]
	v_mfma_f32_16x16x32_bf16 v[64:67], v[186:189], v[220:223], v[64:67]
	s_setprio 0
	s_barrier
; #define PG8_STAGE(bufoff, gbase, voff) do { _Pragma("unroll") for (int _i = 0; _i < 2; ++_i) \
;         __builtin_amdgcn_global_load_lds((const unsigned*)((const char*)(gbase) + (voff)[_i]), (PG8_LAS unsigned*)(lds + (bufoff) + ldsw + _i * 8192), 16, 0, 0); } while (0)
; #define PG8_LDA(dst, b, h) do { _Pragma("unroll") for (int m = 0; m < 4; ++m) _Pragma("unroll") for (int k = 0; k < 2; ++k) dst[m][k] = *(const PG8_LAS bf16x8*)(lds + PG8_SA(b, h) + aoff + m * 2048 + k * 1024); } while (0)
; #define PG8_WAIT_V(n) asm volatile("s_waitcnt vmcnt(" #n ")" ::: "memory")
; #define PG8_BAR __builtin_amdgcn_s_barrier()
; template <class Epi, class Sched, bool ALIGN_EPI = false, bool SP2 = false>
; __device__ __forceinline__ void gemm_phase(PG8_LAS unsigned char* lds, const Gemm g, const Sched& S, const Epi& E) {
;     ...
;         for (int t = 0; t < nt; t += 2) {
;             const bool last = (t == nt - 2);
;             const char* a1 = cA + (size_t)(t + 1) * kstep;
;             const char* a2 = last ? nA : cA + (size_t)(t + 2) * kstep; const char* b2 = last ? nB : cB + (size_t)(t + 2) * kstep;
;             const char* a3 = a2 + kstep; const char* b3 = b2 + kstep;
;             if (last && has_next) S.a_ready(nxt);
;             if constexpr (SP2) {
;             PG8_LDB(B0, 0, 0); PG8_LDB(B1, 0, 1); PG8_SCHED; PG8_LDA(At, 0, 0); PG8_STAGE(PG8_SA(1, 1), a1 + hstepA, voffA);
;             PG8_WAIT_V(8); PG8_WAIT_L(0); PG8_BAR; PG8_MMA(0, 0, At, B0); PG8_MMA(0, 1, At, B1); PG8_BAR; PG8_SCHED;
;             PG8_LDA(At, 0, 1); PG8_STAGE(PG8_SB(0, 0), b2, voffB); PG8_STAGE(PG8_SB(0, 1), b2 + hstepB, voffB); PG8_STAGE(PG8_SA(0, 0), a2, voffA);
;             PG8_WAIT_V(8); PG8_WAIT_L(0); PG8_BAR; PG8_MMA(1, 0, At, B0); PG8_MMA(1, 1, At, B1); PG8_BAR; PG8_SCHED;
;             PG8_LDB(B0, 1, 0); PG8_LDB(B1, 1, 1); PG8_SCHED; PG8_LDA(At, 1, 0); PG8_STAGE(PG8_SA(0, 1), a2 + hstepA, voffA);
;             PG8_WAIT_V(8); PG8_WAIT_L(0); PG8_BAR; PG8_MMA(0, 0, At, B0); PG8_MMA(0, 1, At, B1); PG8_BAR; PG8_SCHED;
;             PG8_LDA(At, 1, 1); PG8_STAGE(PG8_SB(1, 0), b3, voffB); PG8_STAGE(PG8_SB(1, 1), b3 + hstepB, voffB); PG8_STAGE(PG8_SA(1, 0), a3, voffA);
;             PG8_WAIT_V(8); PG8_WAIT_L(0); PG8_BAR; PG8_MMA(1, 0, At, B0); PG8_MMA(1, 1, At, B1); PG8_BAR; PG8_SCHED;
;     ...
;     PG8_WAIT_V(0);
;     if constexpr (!ALIGN_EPI) { if (wr == 0) PG8_BAR; }
	s_add_i32 s36, s70, s2
	v_lshl_add_u64 v[224:225], v[224:225], 0, s[20:21]
	s_mov_b32 m0, s36
	ds_read_b128 v[190:193], v149 offset:49152
	ds_read_b128 v[196:199], v149 offset:50176
	ds_read_b128 v[200:203], v149 offset:51200
	ds_read_b128 v[204:207], v149 offset:52224
	ds_read_b128 v[208:211], v149 offset:53248
	ds_read_b128 v[212:215], v149 offset:54272
	ds_read_b128 v[216:219], v149 offset:55296
	ds_read_b128 v[220:223], v149 offset:56320
	global_load_lds_dwordx4 v[224:225], off
	s_add_i32 m0, s36, 0x2000
	s_add_u32 s34, s34, 0x80080
	v_lshl_add_u64 v[224:225], v[226:227], 0, s[20:21]
	s_addc_u32 s35, s35, 0
	s_add_i32 s36, s71, s2
	global_load_lds_dwordx4 v[224:225], off
	v_lshl_add_u64 v[224:225], s[34:35], 0, v[132:133]
	s_mov_b32 m0, s36
	s_nop 0
	global_load_lds_dwordx4 v[224:225], off
	v_lshl_add_u64 v[224:225], s[34:35], 0, v[138:139]
	s_add_i32 m0, s36, 0x2000
	s_nop 0
	global_load_lds_dwordx4 v[224:225], off
	v_lshl_add_u64 v[224:225], v[228:229], 0, s[20:21]
	s_mov_b32 m0, s63
	s_nop 0
	global_load_lds_dwordx4 v[224:225], off
	v_lshl_add_u64 v[224:225], v[230:231], 0, s[20:21]
	s_mov_b32 m0, s64
	s_nop 0
	global_load_lds_dwordx4 v[224:225], off
	s_waitcnt vmcnt(8)
	s_waitcnt lgkmcnt(0)
	s_barrier
	s_setprio 1
	s_waitcnt lgkmcnt(0)
	v_mfma_f32_16x16x32_bf16 v[60:63], v[150:153], v[190:193], v[60:63]
	v_mfma_f32_16x16x32_bf16 v[56:59], v[158:161], v[190:193], v[56:59]
	v_mfma_f32_16x16x32_bf16 v[52:55], v[150:153], v[200:203], v[52:55]
	v_mfma_f32_16x16x32_bf16 v[48:51], v[158:161], v[200:203], v[48:51]
	v_mfma_f32_16x16x32_bf16 v[36:39], v[150:153], v[208:211], v[36:39]
	v_mfma_f32_16x16x32_bf16 v[32:35], v[158:161], v[208:211], v[32:35]
	v_mfma_f32_16x16x32_bf16 v[20:23], v[150:153], v[216:219], v[20:23]
	v_mfma_f32_16x16x32_bf16 v[16:19], v[158:161], v[216:219], v[16:19]
	v_mfma_f32_16x16x32_bf16 v[60:63], v[154:157], v[196:199], v[60:63]
	v_mfma_f32_16x16x32_bf16 v[56:59], v[170:173], v[196:199], v[56:59]
	v_mfma_f32_16x16x32_bf16 v[52:55], v[154:157], v[204:207], v[52:55]
	v_mfma_f32_16x16x32_bf16 v[48:51], v[170:173], v[204:207], v[48:51]
	v_mfma_f32_16x16x32_bf16 v[36:39], v[154:157], v[212:215], v[36:39]
	v_mfma_f32_16x16x32_bf16 v[32:35], v[170:173], v[212:215], v[32:35]
	v_mfma_f32_16x16x32_bf16 v[20:23], v[154:157], v[220:223], v[20:23]
	v_mfma_f32_16x16x32_bf16 v[16:19], v[170:173], v[220:223], v[16:19]
	v_mfma_f32_16x16x32_bf16 v[44:47], v[174:177], v[190:193], v[44:47]
	v_mfma_f32_16x16x32_bf16 v[40:43], v[182:185], v[190:193], v[40:43]
	v_mfma_f32_16x16x32_bf16 v[28:31], v[174:177], v[200:203], v[28:31]
	v_mfma_f32_16x16x32_bf16 v[24:27], v[182:185], v[200:203], v[24:27]
	v_mfma_f32_16x16x32_bf16 v[12:15], v[174:177], v[208:211], v[12:15]
	v_mfma_f32_16x16x32_bf16 v[8:11], v[182:185], v[208:211], v[8:11]
	v_mfma_f32_16x16x32_bf16 v[4:7], v[174:177], v[216:219], v[4:7]
	v_mfma_f32_16x16x32_bf16 v[0:3], v[182:185], v[216:219], v[0:3]
	v_mfma_f32_16x16x32_bf16 v[44:47], v[178:181], v[196:199], v[44:47]
	v_mfma_f32_16x16x32_bf16 v[40:43], v[186:189], v[196:199], v[40:43]
	v_mfma_f32_16x16x32_bf16 v[28:31], v[178:181], v[204:207], v[28:31]
	v_mfma_f32_16x16x32_bf16 v[24:27], v[186:189], v[204:207], v[24:27]
	v_mfma_f32_16x16x32_bf16 v[12:15], v[178:181], v[212:215], v[12:15]
	v_mfma_f32_16x16x32_bf16 v[8:11], v[186:189], v[212:215], v[8:11]
	v_mfma_f32_16x16x32_bf16 v[4:7], v[178:181], v[220:223], v[4:7]
	v_mfma_f32_16x16x32_bf16 v[0:3], v[186:189], v[220:223], v[0:3]
	s_setprio 0
	s_barrier
	s_add_i32 s69, s69, 2
	s_add_u32 s30, s30, 0x100
	s_addc_u32 s31, s31, 0
	s_cmp_lt_u32 s69, 30
	s_cbranch_scc1 .LBB0_736
	s_waitcnt vmcnt(0)
	s_cmpk_gt_u32 s0, 0xff
	s_cbranch_scc1 .LBB0_739
	s_barrier

; #define PG8_STAGE(bufoff, gbase, voff) do { _Pragma("unroll") for (int _i = 0; _i < 2; ++_i) \
;         __builtin_amdgcn_global_load_lds((const unsigned*)((const char*)(gbase) + (voff)[_i]), (PG8_LAS unsigned*)(lds + (bufoff) + ldsw + _i * 8192), 16, 0, 0); } while (0)
; #define PG8_LDA(dst, b, h) do { _Pragma("unroll") for (int m = 0; m < 4; ++m) _Pragma("unroll") for (int k = 0; k < 2; ++k) dst[m][k] = *(const PG8_LAS bf16x8*)(lds + PG8_SA(b, h) + aoff + m * 2048 + k * 1024); } while (0)
; #define PG8_LDB(dst, b, h) do { _Pragma("unroll") for (int n = 0; n < 2; ++n) _Pragma("unroll") for (int k = 0; k < 2; ++k) dst[n][k] = *(const PG8_LAS bf16x8*)(lds + PG8_SB(b, h) + boff + n * 2048 + k * 1024); } while (0)
; #define PG8_MMA(ai, bj, At, Bt) do { __builtin_amdgcn_s_setprio(1); _Pragma("unroll") for (int m = 0; m < 4; ++m) _Pragma("unroll") for (int n = 0; n < 2; ++n) _Pragma("unroll") for (int k = 0; k < 2; ++k) \
;         acc[ai][bj][m][n] = __builtin_amdgcn_mfma_f32_16x16x32_bf16(Bt[n][k], At[m][k], acc[ai][bj][m][n], 0, 0, 0); __builtin_amdgcn_s_setprio(0); } while (0)
; #define PG8_WAIT_V(n) asm volatile("s_waitcnt vmcnt(" #n ")" ::: "memory")
; #define PG8_WAIT_L(n) asm volatile("s_waitcnt lgkmcnt(" #n ")" ::: "memory")
; #define PG8_BAR __builtin_amdgcn_s_barrier()
; #define PG8_SCHED __builtin_amdgcn_sched_barrier(0)
; template <class Epi, class Sched, bool ALIGN_EPI = false, bool SP2 = false>
; __device__ __forceinline__ void gemm_phase(PG8_LAS unsigned char* lds, const Gemm g, const Sched& S, const Epi& E) {
;     ...
;             const bool last = (t == nt - 2);
;             const char* a1 = cA + (size_t)(t + 1) * kstep;
;             const char* a2 = last ? nA : cA + (size_t)(t + 2) * kstep; const char* b2 = last ? nB : cB + (size_t)(t + 2) * kstep;
;             const char* a3 = a2 + kstep; const char* b3 = b2 + kstep;
;             if (last && has_next) S.a_ready(nxt);
;             if constexpr (SP2) {
;             PG8_LDB(B0, 0, 0); PG8_LDB(B1, 0, 1); PG8_SCHED; PG8_LDA(At, 0, 0); PG8_STAGE(PG8_SA(1, 1), a1 + hstepA, voffA);
;             PG8_WAIT_V(8); PG8_WAIT_L(0); PG8_BAR; PG8_MMA(0, 0, At, B0); PG8_MMA(0, 1, At, B1); PG8_BAR; PG8_SCHED;
;             PG8_LDA(At, 0, 1); PG8_STAGE(PG8_SB(0, 0), b2, voffB); PG8_STAGE(PG8_SB(0, 1), b2 + hstepB, voffB); PG8_STAGE(PG8_SA(0, 0), a2, voffA);
.LBB0_894:
	ds_read_b128 v[64:67], v172
	ds_read_b128 v[108:111], v172 offset:1024
	ds_read_b128 v[116:119], v172 offset:2048
	ds_read_b128 v[128:131], v172 offset:3072
	ds_read_b128 v[156:159], v173
	ds_read_b128 v[176:179], v173 offset:1024
	ds_read_b128 v[180:183], v173 offset:2048
	ds_read_b128 v[184:187], v173 offset:3072
	s_add_u32 s28, s26, 0x100
	s_addc_u32 s29, s27, 0
	s_cmpk_eq_i32 s57, 0x54
	s_cselect_b32 s35, s7, s29
	s_cselect_b32 s34, s6, s28
	s_cselect_b32 s31, s25, s55
	s_cselect_b32 s30, s24, s54
	v_lshl_add_u64 v[160:161], s[26:27], 0, v[148:149]
	s_add_i32 m0, s36, 0xc000
	ds_read_b128 v[188:191], v174
	ds_read_b128 v[196:199], v174 offset:1024
	ds_read_b128 v[200:203], v174 offset:2048
	ds_read_b128 v[204:207], v174 offset:3072
	ds_read_b128 v[208:211], v174 offset:4096
	ds_read_b128 v[212:215], v174 offset:5120
	ds_read_b128 v[216:219], v174 offset:6144
	ds_read_b128 v[220:223], v174 offset:7168
	global_load_lds_dwordx4 v[160:161], off
	v_lshl_add_u64 v[160:161], s[26:27], 0, v[150:151]
	s_add_i32 m0, s36, 0xe000
	s_nop 0
	global_load_lds_dwordx4 v[160:161], off
	s_waitcnt vmcnt(8)
	s_waitcnt lgkmcnt(0)
	s_barrier
	s_setprio 1
	s_waitcnt lgkmcnt(0)
	v_mfma_f32_16x16x32_bf16 v[140:143], v[64:67], v[188:191], v[140:143]
	v_mfma_f32_16x16x32_bf16 v[136:139], v[116:119], v[188:191], v[136:139]
	v_mfma_f32_16x16x32_bf16 v[120:123], v[64:67], v[200:203], v[120:123]
	v_mfma_f32_16x16x32_bf16 v[112:115], v[116:119], v[200:203], v[112:115]
	v_mfma_f32_16x16x32_bf16 v[96:99], v[64:67], v[208:211], v[96:99]
	v_mfma_f32_16x16x32_bf16 v[92:95], v[116:119], v[208:211], v[92:95]
	v_mfma_f32_16x16x32_bf16 v[80:83], v[64:67], v[216:219], v[80:83]
	v_mfma_f32_16x16x32_bf16 v[76:79], v[116:119], v[216:219], v[76:79]
	v_mfma_f32_16x16x32_bf16 v[140:143], v[108:111], v[196:199], v[140:143]
	v_mfma_f32_16x16x32_bf16 v[136:139], v[128:131], v[196:199], v[136:139]
	v_mfma_f32_16x16x32_bf16 v[120:123], v[108:111], v[204:207], v[120:123]
	v_mfma_f32_16x16x32_bf16 v[112:115], v[128:131], v[204:207], v[112:115]
	v_mfma_f32_16x16x32_bf16 v[96:99], v[108:111], v[212:215], v[96:99]
	v_mfma_f32_16x16x32_bf16 v[92:95], v[128:131], v[212:215], v[92:95]
	v_mfma_f32_16x16x32_bf16 v[80:83], v[108:111], v[220:223], v[80:83]
	v_mfma_f32_16x16x32_bf16 v[76:79], v[128:131], v[220:223], v[76:79]
	v_mfma_f32_16x16x32_bf16 v[132:135], v[156:159], v[188:191], v[132:135]
	v_mfma_f32_16x16x32_bf16 v[124:127], v[180:183], v[188:191], v[124:127]
	v_mfma_f32_16x16x32_bf16 v[104:107], v[156:159], v[200:203], v[104:107]
	v_mfma_f32_16x16x32_bf16 v[100:103], v[180:183], v[200:203], v[100:103]
	v_mfma_f32_16x16x32_bf16 v[88:91], v[156:159], v[208:211], v[88:91]
	v_mfma_f32_16x16x32_bf16 v[84:87], v[180:183], v[208:211], v[84:87]
	v_mfma_f32_16x16x32_bf16 v[72:75], v[156:159], v[216:219], v[72:75]
	v_mfma_f32_16x16x32_bf16 v[68:71], v[180:183], v[216:219], v[68:71]
	v_mfma_f32_16x16x32_bf16 v[132:135], v[176:179], v[196:199], v[132:135]
	v_mfma_f32_16x16x32_bf16 v[124:127], v[184:187], v[196:199], v[124:127]
	v_mfma_f32_16x16x32_bf16 v[104:107], v[176:179], v[204:207], v[104:107]
	v_mfma_f32_16x16x32_bf16 v[100:103], v[184:187], v[204:207], v[100:103]
	v_mfma_f32_16x16x32_bf16 v[88:91], v[176:179], v[212:215], v[88:91]
	v_mfma_f32_16x16x32_bf16 v[84:87], v[184:187], v[212:215], v[84:87]
	v_mfma_f32_16x16x32_bf16 v[72:75], v[176:179], v[220:223], v[72:75]
	v_mfma_f32_16x16x32_bf16 v[68:71], v[184:187], v[220:223], v[68:71]
	s_setprio 0
	s_barrier
	s_add_i32 s26, s56, s33
	v_lshl_add_u64 v[160:161], s[30:31], 0, v[146:147]
	s_mov_b32 m0, s26
	ds_read_b128 v[188:191], v174 offset:16384
	ds_read_b128 v[196:199], v174 offset:17408
	ds_read_b128 v[200:203], v174 offset:18432
	ds_read_b128 v[204:207], v174 offset:19456
	ds_read_b128 v[208:211], v174 offset:20480
	ds_read_b128 v[212:215], v174 offset:21504
	ds_read_b128 v[216:219], v174 offset:22528
	ds_read_b128 v[220:223], v174 offset:23552
	global_load_lds_dwordx4 v[160:161], off
	s_add_i32 m0, s26, 0x2000
	s_add_u32 s26, s30, 0x160000
	v_lshl_add_u64 v[192:193], s[30:31], 0, v[144:145]
	s_addc_u32 s27, s31, 0
	s_add_i32 s58, s45, s33
	global_load_lds_dwordx4 v[192:193], off
	v_lshl_add_u64 v[224:225], s[26:27], 0, v[146:147]
	s_mov_b32 m0, s58
	v_lshl_add_u64 v[226:227], s[34:35], 0, v[144:145]
	global_load_lds_dwordx4 v[224:225], off
	v_lshl_add_u64 v[224:225], s[26:27], 0, v[144:145]
	s_add_i32 m0, s58, 0x2000
	s_nop 0
	global_load_lds_dwordx4 v[224:225], off
	v_lshl_add_u64 v[224:225], s[34:35], 0, v[146:147]
	s_mov_b32 m0, s36
	s_nop 0
	global_load_lds_dwordx4 v[224:225], off
	s_mov_b32 m0, s37
	s_nop 0
	global_load_lds_dwordx4 v[226:227], off
	s_waitcnt vmcnt(8)
	s_waitcnt lgkmcnt(0)
	s_barrier
; #define PG8_STAGE(bufoff, gbase, voff) do { _Pragma("unroll") for (int _i = 0; _i < 2; ++_i) \
;         __builtin_amdgcn_global_load_lds((const unsigned*)((const char*)(gbase) + (voff)[_i]), (PG8_LAS unsigned*)(lds + (bufoff) + ldsw + _i * 8192), 16, 0, 0); } while (0)
; #define PG8_LDA(dst, b, h) do { _Pragma("unroll") for (int m = 0; m < 4; ++m) _Pragma("unroll") for (int k = 0; k < 2; ++k) dst[m][k] = *(const PG8_LAS bf16x8*)(lds + PG8_SA(b, h) + aoff + m * 2048 + k * 1024); } while (0)
; #define PG8_LDB(dst, b, h) do { _Pragma("unroll") for (int n = 0; n < 2; ++n) _Pragma("unroll") for (int k = 0; k < 2; ++k) dst[n][k] = *(const PG8_LAS bf16x8*)(lds + PG8_SB(b, h) + boff + n * 2048 + k * 1024); } while (0)
; #define PG8_MMA(ai, bj, At, Bt) do { __builtin_amdgcn_s_setprio(1); _Pragma("unroll") for (int m = 0; m < 4; ++m) _Pragma("unroll") for (int n = 0; n < 2; ++n) _Pragma("unroll") for (int k = 0; k < 2; ++k) \
;         acc[ai][bj][m][n] = __builtin_amdgcn_mfma_f32_16x16x32_bf16(Bt[n][k], At[m][k], acc[ai][bj][m][n], 0, 0, 0); __builtin_amdgcn_s_setprio(0); } while (0)
; #define PG8_WAIT_V(n) asm volatile("s_waitcnt vmcnt(" #n ")" ::: "memory")
; #define PG8_WAIT_L(n) asm volatile("s_waitcnt lgkmcnt(" #n ")" ::: "memory")
; #define PG8_BAR __builtin_amdgcn_s_barrier()
; #define PG8_SCHED __builtin_amdgcn_sched_barrier(0)
; template <class Epi, class Sched, bool ALIGN_EPI = false, bool SP2 = false>
; __device__ __forceinline__ void gemm_phase(PG8_LAS unsigned char* lds, const Gemm g, const Sched& S, const Epi& E) {
;     ...
;             PG8_WAIT_V(8); PG8_WAIT_L(0); PG8_BAR; PG8_MMA(1, 0, At, B0); PG8_MMA(1, 1, At, B1); PG8_BAR; PG8_SCHED;
;             PG8_LDB(B0, 1, 0); PG8_LDB(B1, 1, 1); PG8_SCHED; PG8_LDA(At, 1, 0); PG8_STAGE(PG8_SA(0, 1), a2 + hstepA, voffA);
;             PG8_WAIT_V(8); PG8_WAIT_L(0); PG8_BAR; PG8_MMA(0, 0, At, B0); PG8_MMA(0, 1, At, B1); PG8_BAR; PG8_SCHED;
	s_setprio 1
	s_waitcnt lgkmcnt(0)
	v_mfma_f32_16x16x32_bf16 v[60:63], v[64:67], v[188:191], v[60:63]
	v_mfma_f32_16x16x32_bf16 v[56:59], v[116:119], v[188:191], v[56:59]
	v_mfma_f32_16x16x32_bf16 v[44:47], v[64:67], v[200:203], v[44:47]
	v_mfma_f32_16x16x32_bf16 v[40:43], v[116:119], v[200:203], v[40:43]
	v_mfma_f32_16x16x32_bf16 v[28:31], v[64:67], v[208:211], v[28:31]
	v_mfma_f32_16x16x32_bf16 v[24:27], v[116:119], v[208:211], v[24:27]
	v_mfma_f32_16x16x32_bf16 v[12:15], v[64:67], v[216:219], v[12:15]
	v_mfma_f32_16x16x32_bf16 v[8:11], v[116:119], v[216:219], v[8:11]
	v_mfma_f32_16x16x32_bf16 v[60:63], v[108:111], v[196:199], v[60:63]
	v_mfma_f32_16x16x32_bf16 v[56:59], v[128:131], v[196:199], v[56:59]
	v_mfma_f32_16x16x32_bf16 v[44:47], v[108:111], v[204:207], v[44:47]
	v_mfma_f32_16x16x32_bf16 v[40:43], v[128:131], v[204:207], v[40:43]
	v_mfma_f32_16x16x32_bf16 v[28:31], v[108:111], v[212:215], v[28:31]
	v_mfma_f32_16x16x32_bf16 v[24:27], v[128:131], v[212:215], v[24:27]
	v_mfma_f32_16x16x32_bf16 v[12:15], v[108:111], v[220:223], v[12:15]
	v_mfma_f32_16x16x32_bf16 v[8:11], v[128:131], v[220:223], v[8:11]
	v_mfma_f32_16x16x32_bf16 v[52:55], v[156:159], v[188:191], v[52:55]
	v_mfma_f32_16x16x32_bf16 v[48:51], v[180:183], v[188:191], v[48:51]
	v_mfma_f32_16x16x32_bf16 v[36:39], v[156:159], v[200:203], v[36:39]
	v_mfma_f32_16x16x32_bf16 v[32:35], v[180:183], v[200:203], v[32:35]
	v_mfma_f32_16x16x32_bf16 v[20:23], v[156:159], v[208:211], v[20:23]
	v_mfma_f32_16x16x32_bf16 v[16:19], v[180:183], v[208:211], v[16:19]
	v_mfma_f32_16x16x32_bf16 v[4:7], v[156:159], v[216:219], v[4:7]
	v_mfma_f32_16x16x32_bf16 v[0:3], v[180:183], v[216:219], v[0:3]
	v_mfma_f32_16x16x32_bf16 v[52:55], v[176:179], v[196:199], v[52:55]
	v_mfma_f32_16x16x32_bf16 v[48:51], v[184:187], v[196:199], v[48:51]
	v_mfma_f32_16x16x32_bf16 v[36:39], v[176:179], v[204:207], v[36:39]
	v_mfma_f32_16x16x32_bf16 v[32:35], v[184:187], v[204:207], v[32:35]
	v_mfma_f32_16x16x32_bf16 v[20:23], v[176:179], v[212:215], v[20:23]
	v_mfma_f32_16x16x32_bf16 v[16:19], v[184:187], v[212:215], v[16:19]
	v_mfma_f32_16x16x32_bf16 v[4:7], v[176:179], v[220:223], v[4:7]
	v_mfma_f32_16x16x32_bf16 v[0:3], v[184:187], v[220:223], v[0:3]
	s_setprio 0
	s_barrier
	s_add_i32 s58, 0, 0x18000
	s_add_i32 s59, 0, 0x1c000
	v_add_u32_e32 v128, s58, v170
	v_add_u32_e32 v175, s59, v170
	ds_read_b128 v[64:67], v128
	ds_read_b128 v[108:111], v128 offset:1024
	ds_read_b128 v[116:119], v128 offset:2048
	ds_read_b128 v[128:131], v128 offset:3072
	ds_read_b128 v[156:159], v175
	ds_read_b128 v[176:179], v175 offset:1024
	ds_read_b128 v[180:183], v175 offset:2048
	ds_read_b128 v[184:187], v175 offset:3072
	s_add_u32 s26, s34, 0x160000
	s_addc_u32 s27, s35, 0
	s_mov_b32 m0, s38
	v_lshl_add_u64 v[228:229], s[26:27], 0, v[146:147]
	ds_read_b128 v[188:191], v174 offset:32768
	ds_read_b128 v[196:199], v174 offset:33792
	ds_read_b128 v[200:203], v174 offset:34816
	ds_read_b128 v[204:207], v174 offset:35840
	ds_read_b128 v[208:211], v174 offset:36864
	ds_read_b128 v[212:215], v174 offset:37888
	ds_read_b128 v[216:219], v174 offset:38912
	ds_read_b128 v[220:223], v174 offset:39936
	global_load_lds_dwordx4 v[228:229], off
	v_lshl_add_u64 v[228:229], s[26:27], 0, v[144:145]
	s_mov_b32 m0, s39
	s_nop 0
	global_load_lds_dwordx4 v[228:229], off
	s_waitcnt vmcnt(8)
	s_waitcnt lgkmcnt(0)
	s_barrier
	s_setprio 1
	s_waitcnt lgkmcnt(0)
	v_mfma_f32_16x16x32_bf16 v[140:143], v[64:67], v[188:191], v[140:143]
	v_mfma_f32_16x16x32_bf16 v[136:139], v[116:119], v[188:191], v[136:139]
	v_mfma_f32_16x16x32_bf16 v[120:123], v[64:67], v[200:203], v[120:123]
	v_mfma_f32_16x16x32_bf16 v[112:115], v[116:119], v[200:203], v[112:115]
	v_mfma_f32_16x16x32_bf16 v[96:99], v[64:67], v[208:211], v[96:99]
	v_mfma_f32_16x16x32_bf16 v[92:95], v[116:119], v[208:211], v[92:95]
	v_mfma_f32_16x16x32_bf16 v[80:83], v[64:67], v[216:219], v[80:83]
	v_mfma_f32_16x16x32_bf16 v[76:79], v[116:119], v[216:219], v[76:79]
	v_mfma_f32_16x16x32_bf16 v[140:143], v[108:111], v[196:199], v[140:143]
	v_mfma_f32_16x16x32_bf16 v[136:139], v[128:131], v[196:199], v[136:139]
	v_mfma_f32_16x16x32_bf16 v[120:123], v[108:111], v[204:207], v[120:123]
	v_mfma_f32_16x16x32_bf16 v[112:115], v[128:131], v[204:207], v[112:115]
	v_mfma_f32_16x16x32_bf16 v[96:99], v[108:111], v[212:215], v[96:99]
	v_mfma_f32_16x16x32_bf16 v[92:95], v[128:131], v[212:215], v[92:95]
	v_mfma_f32_16x16x32_bf16 v[80:83], v[108:111], v[220:223], v[80:83]
	v_mfma_f32_16x16x32_bf16 v[76:79], v[128:131], v[220:223], v[76:79]
	v_mfma_f32_16x16x32_bf16 v[132:135], v[156:159], v[188:191], v[132:135]
	v_mfma_f32_16x16x32_bf16 v[124:127], v[180:183], v[188:191], v[124:127]
	v_mfma_f32_16x16x32_bf16 v[104:107], v[156:159], v[200:203], v[104:107]
	v_mfma_f32_16x16x32_bf16 v[100:103], v[180:183], v[200:203], v[100:103]
	v_mfma_f32_16x16x32_bf16 v[88:91], v[156:159], v[208:211], v[88:91]
	v_mfma_f32_16x16x32_bf16 v[84:87], v[180:183], v[208:211], v[84:87]
	v_mfma_f32_16x16x32_bf16 v[72:75], v[156:159], v[216:219], v[72:75]
	v_mfma_f32_16x16x32_bf16 v[68:71], v[180:183], v[216:219], v[68:71]
	v_mfma_f32_16x16x32_bf16 v[132:135], v[176:179], v[196:199], v[132:135]
	v_mfma_f32_16x16x32_bf16 v[124:127], v[184:187], v[196:199], v[124:127]
	v_mfma_f32_16x16x32_bf16 v[104:107], v[176:179], v[204:207], v[104:107]
	v_mfma_f32_16x16x32_bf16 v[100:103], v[184:187], v[204:207], v[100:103]
	v_mfma_f32_16x16x32_bf16 v[88:91], v[176:179], v[212:215], v[88:91]
	v_mfma_f32_16x16x32_bf16 v[84:87], v[184:187], v[212:215], v[84:87]
	v_mfma_f32_16x16x32_bf16 v[72:75], v[176:179], v[220:223], v[72:75]
	v_mfma_f32_16x16x32_bf16 v[68:71], v[184:187], v[220:223], v[68:71]
	s_setprio 0
	s_barrier
; #define PG8_STAGE(bufoff, gbase, voff) do { _Pragma("unroll") for (int _i = 0; _i < 2; ++_i) \
;         __builtin_amdgcn_global_load_lds((const unsigned*)((const char*)(gbase) + (voff)[_i]), (PG8_LAS unsigned*)(lds + (bufoff) + ldsw + _i * 8192), 16, 0, 0); } while (0)
; #define PG8_LDA(dst, b, h) do { _Pragma("unroll") for (int m = 0; m < 4; ++m) _Pragma("unroll") for (int k = 0; k < 2; ++k) dst[m][k] = *(const PG8_LAS bf16x8*)(lds + PG8_SA(b, h) + aoff + m * 2048 + k * 1024); } while (0)
; #define PG8_WAIT_V(n) asm volatile("s_waitcnt vmcnt(" #n ")" ::: "memory")
; #define PG8_WAIT_L(n) asm volatile("s_waitcnt lgkmcnt(" #n ")" ::: "memory")
; template <class Epi, class Sched, bool ALIGN_EPI = false, bool SP2 = false>
; __device__ __forceinline__ void gemm_phase(PG8_LAS unsigned char* lds, const Gemm g, const Sched& S, const Epi& E) {
;     ...
;         for (int t = 0; t < nt; t += 2) {
;             const bool last = (t == nt - 2);
;             const char* a1 = cA + (size_t)(t + 1) * kstep;
;             const char* a2 = last ? nA : cA + (size_t)(t + 2) * kstep; const char* b2 = last ? nB : cB + (size_t)(t + 2) * kstep;
;             const char* a3 = a2 + kstep; const char* b3 = b2 + kstep;
;             if (last && has_next) S.a_ready(nxt);
;             if constexpr (SP2) {
;             PG8_LDB(B0, 0, 0); PG8_LDB(B1, 0, 1); PG8_SCHED; PG8_LDA(At, 0, 0); PG8_STAGE(PG8_SA(1, 1), a1 + hstepA, voffA);
;             PG8_WAIT_V(8); PG8_WAIT_L(0); PG8_BAR; PG8_MMA(0, 0, At, B0); PG8_MMA(0, 1, At, B1); PG8_BAR; PG8_SCHED;
;             PG8_LDA(At, 0, 1); PG8_STAGE(PG8_SB(0, 0), b2, voffB); PG8_STAGE(PG8_SB(0, 1), b2 + hstepB, voffB); PG8_STAGE(PG8_SA(0, 0), a2, voffA);
;             PG8_WAIT_V(8); PG8_WAIT_L(0); PG8_BAR; PG8_MMA(1, 0, At, B0); PG8_MMA(1, 1, At, B1); PG8_BAR; PG8_SCHED;
;             PG8_LDB(B0, 1, 0); PG8_LDB(B1, 1, 1); PG8_SCHED; PG8_LDA(At, 1, 0); PG8_STAGE(PG8_SA(0, 1), a2 + hstepA, voffA);
;             PG8_WAIT_V(8); PG8_WAIT_L(0); PG8_BAR; PG8_MMA(0, 0, At, B0); PG8_MMA(0, 1, At, B1); PG8_BAR; PG8_SCHED;
;             PG8_LDA(At, 1, 1); PG8_STAGE(PG8_SB(1, 0), b3, voffB); PG8_STAGE(PG8_SB(1, 1), b3 + hstepB, voffB); PG8_STAGE(PG8_SA(1, 0), a3, voffA);
;             PG8_WAIT_V(8); PG8_WAIT_L(0); PG8_BAR; PG8_MMA(1, 0, At, B0); PG8_MMA(1, 1, At, B1); PG8_BAR; PG8_SCHED;
;     ...
;         if constexpr (ALIGN_EPI) { if (wr == 0) PG8_BAR; }
	s_add_i32 s26, s58, s33
	v_lshl_add_u64 v[160:161], v[160:161], 0, s[10:11]
	s_mov_b32 m0, s26
	ds_read_b128 v[188:191], v174 offset:49152
	ds_read_b128 v[196:199], v174 offset:50176
	ds_read_b128 v[200:203], v174 offset:51200
	ds_read_b128 v[204:207], v174 offset:52224
	ds_read_b128 v[208:211], v174 offset:53248
	ds_read_b128 v[212:215], v174 offset:54272
	ds_read_b128 v[216:219], v174 offset:55296
	ds_read_b128 v[220:223], v174 offset:56320
	global_load_lds_dwordx4 v[160:161], off
	s_add_i32 m0, s26, 0x2000
	s_add_u32 s26, s30, 0x160080
	v_lshl_add_u64 v[160:161], v[192:193], 0, s[10:11]
	s_addc_u32 s27, s31, 0
	s_add_i32 s30, s59, s33
	global_load_lds_dwordx4 v[160:161], off
	v_lshl_add_u64 v[160:161], s[26:27], 0, v[146:147]
	s_mov_b32 m0, s30
	s_nop 0
	global_load_lds_dwordx4 v[160:161], off
	v_lshl_add_u64 v[160:161], s[26:27], 0, v[144:145]
	s_add_i32 m0, s30, 0x2000
	s_nop 0
	global_load_lds_dwordx4 v[160:161], off
	v_lshl_add_u64 v[160:161], v[224:225], 0, s[10:11]
	s_mov_b32 m0, s43
	s_nop 0
	global_load_lds_dwordx4 v[160:161], off
	v_lshl_add_u64 v[160:161], v[226:227], 0, s[10:11]
	s_mov_b32 m0, s44
	s_nop 0
	global_load_lds_dwordx4 v[160:161], off
	s_waitcnt vmcnt(8)
	s_waitcnt lgkmcnt(0)
	s_barrier
	s_setprio 1
	s_waitcnt lgkmcnt(0)
	v_mfma_f32_16x16x32_bf16 v[60:63], v[64:67], v[188:191], v[60:63]
	v_mfma_f32_16x16x32_bf16 v[56:59], v[116:119], v[188:191], v[56:59]
	v_mfma_f32_16x16x32_bf16 v[44:47], v[64:67], v[200:203], v[44:47]
	v_mfma_f32_16x16x32_bf16 v[40:43], v[116:119], v[200:203], v[40:43]
	v_mfma_f32_16x16x32_bf16 v[28:31], v[64:67], v[208:211], v[28:31]
	v_mfma_f32_16x16x32_bf16 v[24:27], v[116:119], v[208:211], v[24:27]
	v_mfma_f32_16x16x32_bf16 v[12:15], v[64:67], v[216:219], v[12:15]
	v_mfma_f32_16x16x32_bf16 v[8:11], v[116:119], v[216:219], v[8:11]
	v_mfma_f32_16x16x32_bf16 v[60:63], v[108:111], v[196:199], v[60:63]
	v_mfma_f32_16x16x32_bf16 v[56:59], v[128:131], v[196:199], v[56:59]
	v_mfma_f32_16x16x32_bf16 v[44:47], v[108:111], v[204:207], v[44:47]
	v_mfma_f32_16x16x32_bf16 v[40:43], v[128:131], v[204:207], v[40:43]
	v_mfma_f32_16x16x32_bf16 v[28:31], v[108:111], v[212:215], v[28:31]
	v_mfma_f32_16x16x32_bf16 v[24:27], v[128:131], v[212:215], v[24:27]
	v_mfma_f32_16x16x32_bf16 v[12:15], v[108:111], v[220:223], v[12:15]
	v_mfma_f32_16x16x32_bf16 v[8:11], v[128:131], v[220:223], v[8:11]
	v_mfma_f32_16x16x32_bf16 v[52:55], v[156:159], v[188:191], v[52:55]
	v_mfma_f32_16x16x32_bf16 v[48:51], v[180:183], v[188:191], v[48:51]
	v_mfma_f32_16x16x32_bf16 v[36:39], v[156:159], v[200:203], v[36:39]
	v_mfma_f32_16x16x32_bf16 v[32:35], v[180:183], v[200:203], v[32:35]
	v_mfma_f32_16x16x32_bf16 v[20:23], v[156:159], v[208:211], v[20:23]
	v_mfma_f32_16x16x32_bf16 v[16:19], v[180:183], v[208:211], v[16:19]
	v_mfma_f32_16x16x32_bf16 v[4:7], v[156:159], v[216:219], v[4:7]
	v_mfma_f32_16x16x32_bf16 v[0:3], v[180:183], v[216:219], v[0:3]
	v_mfma_f32_16x16x32_bf16 v[52:55], v[176:179], v[196:199], v[52:55]
	v_mfma_f32_16x16x32_bf16 v[48:51], v[184:187], v[196:199], v[48:51]
	v_mfma_f32_16x16x32_bf16 v[36:39], v[176:179], v[204:207], v[36:39]
	v_mfma_f32_16x16x32_bf16 v[32:35], v[184:187], v[204:207], v[32:35]
	v_mfma_f32_16x16x32_bf16 v[20:23], v[176:179], v[212:215], v[20:23]
	v_mfma_f32_16x16x32_bf16 v[16:19], v[184:187], v[212:215], v[16:19]
	v_mfma_f32_16x16x32_bf16 v[4:7], v[176:179], v[220:223], v[4:7]
	v_mfma_f32_16x16x32_bf16 v[0:3], v[184:187], v[220:223], v[0:3]
	s_setprio 0
	s_barrier
	s_add_i32 s57, s57, 2
	s_add_u32 s54, s54, 0x100
	s_addc_u32 s55, s55, 0
	s_cmpk_gt_u32 s57, 0x55
	s_mov_b64 s[26:27], s[28:29]
	s_cbranch_scc0 .LBB0_894
	s_and_b64 vcc, exec, s[16:17]
	s_cbranch_vccz .LBB0_897
	s_barrier
